# GEMM K-loops (7 of 13): LDS-DMA addresses from SALU bases (saddr form) instead of VALU 64-bit adds; plus attention DMA placement
# baseline (speedup 1.0000x reference)
.LBB0_109:
	ds_read_b128 v[168:171], v151
	ds_read_b128 v[172:175], v152
	ds_read_b128 v[176:179], v153
	ds_read_b128 v[180:183], v154
	ds_read_b128 v[184:187], v155
	ds_read_b128 v[188:191], v156
	ds_read_b128 v[192:195], v157
	ds_read_b128 v[196:199], v158
	s_add_u32 s26, s4, 0xfff80080
	s_addc_u32 s27, s5, -1
	s_cmp_eq_u32 s88, 28
	s_cselect_b32 s63, s37, s27
	s_cselect_b32 s62, s84, s26
	s_cselect_b32 s61, s55, s87
	s_cselect_b32 s60, s85, s86
	s_add_i32 m0, s66, 0xc000
	ds_read_b128 v[200:203], v159
	ds_read_b128 v[204:207], v159 offset:2048
	ds_read_b128 v[208:211], v160
	ds_read_b128 v[212:215], v160 offset:2048
	ds_read_b128 v[216:219], v159 offset:4096
	ds_read_b128 v[220:223], v159 offset:6144
	ds_read_b128 v[228:231], v160 offset:4096
	ds_read_b128 v[232:235], v160 offset:6144
	global_load_lds_dwordx4 v136, s[4:5]
	s_add_i32 m0, s66, 0xe000
	s_nop 0
	global_load_lds_dwordx4 v138, s[4:5]
	s_waitcnt vmcnt(8)
	s_waitcnt lgkmcnt(0)
	s_barrier
	s_setprio 1
	s_waitcnt lgkmcnt(0)
	v_mfma_f32_16x16x32_bf16 v[124:127], v[168:171], v[200:203], v[124:127]
	v_mfma_f32_16x16x32_bf16 v[116:119], v[176:179], v[200:203], v[116:119]
	v_mfma_f32_16x16x32_bf16 v[108:111], v[168:171], v[204:207], v[108:111]
	v_mfma_f32_16x16x32_bf16 v[100:103], v[176:179], v[204:207], v[100:103]
	v_mfma_f32_16x16x32_bf16 v[92:95], v[168:171], v[216:219], v[92:95]
	v_mfma_f32_16x16x32_bf16 v[84:87], v[176:179], v[216:219], v[84:87]
	v_mfma_f32_16x16x32_bf16 v[76:79], v[168:171], v[220:223], v[76:79]
	v_mfma_f32_16x16x32_bf16 v[68:71], v[176:179], v[220:223], v[68:71]
	v_mfma_f32_16x16x32_bf16 v[124:127], v[172:175], v[208:211], v[124:127]
	v_mfma_f32_16x16x32_bf16 v[116:119], v[180:183], v[208:211], v[116:119]
	v_mfma_f32_16x16x32_bf16 v[108:111], v[172:175], v[212:215], v[108:111]
	v_mfma_f32_16x16x32_bf16 v[100:103], v[180:183], v[212:215], v[100:103]
	v_mfma_f32_16x16x32_bf16 v[92:95], v[172:175], v[228:231], v[92:95]
	v_mfma_f32_16x16x32_bf16 v[84:87], v[180:183], v[228:231], v[84:87]
	v_mfma_f32_16x16x32_bf16 v[76:79], v[172:175], v[232:235], v[76:79]
	v_mfma_f32_16x16x32_bf16 v[68:71], v[180:183], v[232:235], v[68:71]
	s_setprio 0
	s_setprio 1
	v_mfma_f32_16x16x32_bf16 v[120:123], v[184:187], v[200:203], v[120:123]
	v_mfma_f32_16x16x32_bf16 v[112:115], v[192:195], v[200:203], v[112:115]
	v_mfma_f32_16x16x32_bf16 v[104:107], v[184:187], v[204:207], v[104:107]
	v_mfma_f32_16x16x32_bf16 v[96:99], v[192:195], v[204:207], v[96:99]
	v_mfma_f32_16x16x32_bf16 v[88:91], v[184:187], v[216:219], v[88:91]
	v_mfma_f32_16x16x32_bf16 v[80:83], v[192:195], v[216:219], v[80:83]
	v_mfma_f32_16x16x32_bf16 v[72:75], v[184:187], v[220:223], v[72:75]
	v_mfma_f32_16x16x32_bf16 v[64:67], v[192:195], v[220:223], v[64:67]
	v_mfma_f32_16x16x32_bf16 v[120:123], v[188:191], v[208:211], v[120:123]
	v_mfma_f32_16x16x32_bf16 v[112:115], v[196:199], v[208:211], v[112:115]
	v_mfma_f32_16x16x32_bf16 v[104:107], v[188:191], v[212:215], v[104:107]
	v_mfma_f32_16x16x32_bf16 v[96:99], v[196:199], v[212:215], v[96:99]
	v_mfma_f32_16x16x32_bf16 v[88:91], v[188:191], v[228:231], v[88:91]
	v_mfma_f32_16x16x32_bf16 v[80:83], v[196:199], v[228:231], v[80:83]
	v_mfma_f32_16x16x32_bf16 v[72:75], v[188:191], v[232:235], v[72:75]
	v_mfma_f32_16x16x32_bf16 v[64:67], v[196:199], v[232:235], v[64:67]
	s_setprio 0
	s_barrier
	s_add_i32 s26, s75, s64
	s_mov_b32 m0, s26
	ds_read_b128 v[200:203], v159 offset:16384
	ds_read_b128 v[204:207], v159 offset:18432
	ds_read_b128 v[208:211], v160 offset:16384
	ds_read_b128 v[212:215], v160 offset:18432
	ds_read_b128 v[216:219], v159 offset:20480
	ds_read_b128 v[220:223], v159 offset:22528
	ds_read_b128 v[228:231], v160 offset:20480
	ds_read_b128 v[232:235], v160 offset:22528
	global_load_lds_dwordx4 v132, s[60:61]
	s_add_i32 m0, s26, 0x2000
	s_add_u32 s90, s60, 0x80000
	s_addc_u32 s91, s61, 0
	s_add_i32 s26, s78, s64
	global_load_lds_dwordx4 v128, s[60:61]
	s_mov_b32 m0, s26
	s_nop 0
	global_load_lds_dwordx4 v132, s[90:91]
	s_add_i32 m0, s26, 0x2000
	s_nop 0
	global_load_lds_dwordx4 v128, s[90:91]
	s_mov_b32 m0, s66
	s_nop 0
	global_load_lds_dwordx4 v134, s[62:63]
	s_mov_b32 m0, s67
	s_nop 0
	global_load_lds_dwordx4 v130, s[62:63]
	s_waitcnt vmcnt(8)
	s_waitcnt lgkmcnt(0)
	s_barrier
	s_setprio 1
	s_waitcnt lgkmcnt(0)
	v_mfma_f32_16x16x32_bf16 v[60:63], v[168:171], v[200:203], v[60:63]
	v_mfma_f32_16x16x32_bf16 v[52:55], v[176:179], v[200:203], v[52:55]
	v_mfma_f32_16x16x32_bf16 v[44:47], v[168:171], v[204:207], v[44:47]
	v_mfma_f32_16x16x32_bf16 v[36:39], v[176:179], v[204:207], v[36:39]
	v_mfma_f32_16x16x32_bf16 v[28:31], v[168:171], v[216:219], v[28:31]
	v_mfma_f32_16x16x32_bf16 v[20:23], v[176:179], v[216:219], v[20:23]
	v_mfma_f32_16x16x32_bf16 v[12:15], v[168:171], v[220:223], v[12:15]
	v_mfma_f32_16x16x32_bf16 v[4:7], v[176:179], v[220:223], v[4:7]
	v_mfma_f32_16x16x32_bf16 v[60:63], v[172:175], v[208:211], v[60:63]
	v_mfma_f32_16x16x32_bf16 v[52:55], v[180:183], v[208:211], v[52:55]
	v_mfma_f32_16x16x32_bf16 v[44:47], v[172:175], v[212:215], v[44:47]
	v_mfma_f32_16x16x32_bf16 v[36:39], v[180:183], v[212:215], v[36:39]
	v_mfma_f32_16x16x32_bf16 v[28:31], v[172:175], v[228:231], v[28:31]
	v_mfma_f32_16x16x32_bf16 v[20:23], v[180:183], v[228:231], v[20:23]
	v_mfma_f32_16x16x32_bf16 v[12:15], v[172:175], v[232:235], v[12:15]
	v_mfma_f32_16x16x32_bf16 v[4:7], v[180:183], v[232:235], v[4:7]
	s_setprio 0
	s_setprio 1
	v_mfma_f32_16x16x32_bf16 v[56:59], v[184:187], v[200:203], v[56:59]
	v_mfma_f32_16x16x32_bf16 v[48:51], v[192:195], v[200:203], v[48:51]
	v_mfma_f32_16x16x32_bf16 v[40:43], v[184:187], v[204:207], v[40:43]
	v_mfma_f32_16x16x32_bf16 v[32:35], v[192:195], v[204:207], v[32:35]
	v_mfma_f32_16x16x32_bf16 v[24:27], v[184:187], v[216:219], v[24:27]
	v_mfma_f32_16x16x32_bf16 v[16:19], v[192:195], v[216:219], v[16:19]
	v_mfma_f32_16x16x32_bf16 v[8:11], v[184:187], v[220:223], v[8:11]
	v_mfma_f32_16x16x32_bf16 v[0:3], v[192:195], v[220:223], v[0:3]
	v_mfma_f32_16x16x32_bf16 v[56:59], v[188:191], v[208:211], v[56:59]
	v_mfma_f32_16x16x32_bf16 v[48:51], v[196:199], v[208:211], v[48:51]
	v_mfma_f32_16x16x32_bf16 v[40:43], v[188:191], v[212:215], v[40:43]
	v_mfma_f32_16x16x32_bf16 v[32:35], v[196:199], v[212:215], v[32:35]
	v_mfma_f32_16x16x32_bf16 v[24:27], v[188:191], v[228:231], v[24:27]
	v_mfma_f32_16x16x32_bf16 v[16:19], v[196:199], v[228:231], v[16:19]
	v_mfma_f32_16x16x32_bf16 v[8:11], v[188:191], v[232:235], v[8:11]
	v_mfma_f32_16x16x32_bf16 v[0:3], v[196:199], v[232:235], v[0:3]
	s_setprio 0
	s_barrier
	s_add_i32 s26, 0, 0x18000
	v_add_u32_e32 v167, s26, v146
	v_add_u32_e32 v172, s26, v147
	s_add_i32 s27, 0, 0x1c000
	ds_read_b128 v[168:171], v167
	ds_read_b128 v[172:175], v172
	ds_read_b128 v[176:179], v161
	ds_read_b128 v[180:183], v162
	v_add_u32_e32 v167, s27, v146
	v_add_u32_e32 v188, s27, v147
	ds_read_b128 v[184:187], v167
	ds_read_b128 v[188:191], v188
	ds_read_b128 v[192:195], v163
	ds_read_b128 v[196:199], v164
	s_add_u32 s62, s62, 0x80000
	s_addc_u32 s63, s63, 0
	s_mov_b32 m0, s68
	ds_read_b128 v[200:203], v159 offset:32768
	ds_read_b128 v[204:207], v159 offset:34816
	ds_read_b128 v[208:211], v160 offset:32768
	ds_read_b128 v[212:215], v160 offset:34816
	ds_read_b128 v[216:219], v159 offset:36864
	ds_read_b128 v[220:223], v159 offset:38912
	ds_read_b128 v[228:231], v160 offset:36864
	ds_read_b128 v[232:235], v160 offset:38912
	global_load_lds_dwordx4 v134, s[62:63]
	s_mov_b32 m0, s69
	s_nop 0
	global_load_lds_dwordx4 v130, s[62:63]
	s_waitcnt vmcnt(8)
	s_waitcnt lgkmcnt(0)
	s_barrier
	s_setprio 1
	s_waitcnt lgkmcnt(0)
	v_mfma_f32_16x16x32_bf16 v[124:127], v[168:171], v[200:203], v[124:127]
	v_mfma_f32_16x16x32_bf16 v[116:119], v[176:179], v[200:203], v[116:119]
	v_mfma_f32_16x16x32_bf16 v[108:111], v[168:171], v[204:207], v[108:111]
	v_mfma_f32_16x16x32_bf16 v[100:103], v[176:179], v[204:207], v[100:103]
	v_mfma_f32_16x16x32_bf16 v[92:95], v[168:171], v[216:219], v[92:95]
	v_mfma_f32_16x16x32_bf16 v[84:87], v[176:179], v[216:219], v[84:87]
	v_mfma_f32_16x16x32_bf16 v[76:79], v[168:171], v[220:223], v[76:79]
	v_mfma_f32_16x16x32_bf16 v[68:71], v[176:179], v[220:223], v[68:71]
	v_mfma_f32_16x16x32_bf16 v[124:127], v[172:175], v[208:211], v[124:127]
	v_mfma_f32_16x16x32_bf16 v[116:119], v[180:183], v[208:211], v[116:119]
	v_mfma_f32_16x16x32_bf16 v[108:111], v[172:175], v[212:215], v[108:111]
	v_mfma_f32_16x16x32_bf16 v[100:103], v[180:183], v[212:215], v[100:103]
	v_mfma_f32_16x16x32_bf16 v[92:95], v[172:175], v[228:231], v[92:95]
	v_mfma_f32_16x16x32_bf16 v[84:87], v[180:183], v[228:231], v[84:87]
	v_mfma_f32_16x16x32_bf16 v[76:79], v[172:175], v[232:235], v[76:79]
	v_mfma_f32_16x16x32_bf16 v[68:71], v[180:183], v[232:235], v[68:71]
	s_setprio 0
	s_setprio 1
	v_mfma_f32_16x16x32_bf16 v[120:123], v[184:187], v[200:203], v[120:123]
	v_mfma_f32_16x16x32_bf16 v[112:115], v[192:195], v[200:203], v[112:115]
	v_mfma_f32_16x16x32_bf16 v[104:107], v[184:187], v[204:207], v[104:107]
	v_mfma_f32_16x16x32_bf16 v[96:99], v[192:195], v[204:207], v[96:99]
	v_mfma_f32_16x16x32_bf16 v[88:91], v[184:187], v[216:219], v[88:91]
	v_mfma_f32_16x16x32_bf16 v[80:83], v[192:195], v[216:219], v[80:83]
	v_mfma_f32_16x16x32_bf16 v[72:75], v[184:187], v[220:223], v[72:75]
	v_mfma_f32_16x16x32_bf16 v[64:67], v[192:195], v[220:223], v[64:67]
	v_mfma_f32_16x16x32_bf16 v[120:123], v[188:191], v[208:211], v[120:123]
	v_mfma_f32_16x16x32_bf16 v[112:115], v[196:199], v[208:211], v[112:115]
	v_mfma_f32_16x16x32_bf16 v[104:107], v[188:191], v[212:215], v[104:107]
	v_mfma_f32_16x16x32_bf16 v[96:99], v[196:199], v[212:215], v[96:99]
	v_mfma_f32_16x16x32_bf16 v[88:91], v[188:191], v[228:231], v[88:91]
	v_mfma_f32_16x16x32_bf16 v[80:83], v[196:199], v[228:231], v[80:83]
	v_mfma_f32_16x16x32_bf16 v[72:75], v[188:191], v[232:235], v[72:75]
	v_mfma_f32_16x16x32_bf16 v[64:67], v[196:199], v[232:235], v[64:67]
	s_setprio 0
	s_barrier
	s_add_i32 s26, s26, s64
	s_add_i32 m0, s26, 0xffffff80
	ds_read_b128 v[200:203], v159 offset:49152
	ds_read_b128 v[204:207], v159 offset:51200
	ds_read_b128 v[208:211], v160 offset:49152
	ds_read_b128 v[212:215], v160 offset:51200
	ds_read_b128 v[216:219], v159 offset:53248
	ds_read_b128 v[220:223], v159 offset:55296
	ds_read_b128 v[228:231], v160 offset:53248
	ds_read_b128 v[232:235], v160 offset:55296
	global_load_lds_dwordx4 v132, s[60:61] offset:128
	s_add_i32 m0, s26, 0x1f80
	s_add_i32 s26, s27, s64
	global_load_lds_dwordx4 v128, s[60:61] offset:128
	s_add_u32 s60, s60, 0x80080
	s_addc_u32 s61, s61, 0
	s_mov_b32 m0, s26
	s_nop 0
	global_load_lds_dwordx4 v132, s[60:61]
	s_add_i32 m0, s26, 0x2000
	s_nop 0
	global_load_lds_dwordx4 v128, s[60:61]
	s_add_u32 s90, s62, 0xfff80080
	s_addc_u32 s91, s63, -1
	s_mov_b32 m0, s71
	s_nop 0
	global_load_lds_dwordx4 v134, s[90:91]
	s_mov_b32 m0, s72
	s_nop 0
	global_load_lds_dwordx4 v130, s[90:91]
	s_waitcnt vmcnt(8)
	s_waitcnt lgkmcnt(0)
	s_barrier
	s_setprio 1
	s_waitcnt lgkmcnt(0)
	v_mfma_f32_16x16x32_bf16 v[60:63], v[168:171], v[200:203], v[60:63]
	v_mfma_f32_16x16x32_bf16 v[52:55], v[176:179], v[200:203], v[52:55]
	v_mfma_f32_16x16x32_bf16 v[44:47], v[168:171], v[204:207], v[44:47]
	v_mfma_f32_16x16x32_bf16 v[36:39], v[176:179], v[204:207], v[36:39]
	v_mfma_f32_16x16x32_bf16 v[28:31], v[168:171], v[216:219], v[28:31]
	v_mfma_f32_16x16x32_bf16 v[20:23], v[176:179], v[216:219], v[20:23]
	v_mfma_f32_16x16x32_bf16 v[12:15], v[168:171], v[220:223], v[12:15]
	v_mfma_f32_16x16x32_bf16 v[4:7], v[176:179], v[220:223], v[4:7]
	v_mfma_f32_16x16x32_bf16 v[60:63], v[172:175], v[208:211], v[60:63]
	v_mfma_f32_16x16x32_bf16 v[52:55], v[180:183], v[208:211], v[52:55]
	v_mfma_f32_16x16x32_bf16 v[44:47], v[172:175], v[212:215], v[44:47]
	v_mfma_f32_16x16x32_bf16 v[36:39], v[180:183], v[212:215], v[36:39]
	v_mfma_f32_16x16x32_bf16 v[28:31], v[172:175], v[228:231], v[28:31]
	v_mfma_f32_16x16x32_bf16 v[20:23], v[180:183], v[228:231], v[20:23]
	v_mfma_f32_16x16x32_bf16 v[12:15], v[172:175], v[232:235], v[12:15]
	v_mfma_f32_16x16x32_bf16 v[4:7], v[180:183], v[232:235], v[4:7]
	s_setprio 0
	s_setprio 1
	v_mfma_f32_16x16x32_bf16 v[56:59], v[184:187], v[200:203], v[56:59]
	v_mfma_f32_16x16x32_bf16 v[48:51], v[192:195], v[200:203], v[48:51]
	v_mfma_f32_16x16x32_bf16 v[40:43], v[184:187], v[204:207], v[40:43]
	v_mfma_f32_16x16x32_bf16 v[32:35], v[192:195], v[204:207], v[32:35]
	v_mfma_f32_16x16x32_bf16 v[24:27], v[184:187], v[216:219], v[24:27]
	v_mfma_f32_16x16x32_bf16 v[16:19], v[192:195], v[216:219], v[16:19]
	v_mfma_f32_16x16x32_bf16 v[8:11], v[184:187], v[220:223], v[8:11]
	v_mfma_f32_16x16x32_bf16 v[0:3], v[192:195], v[220:223], v[0:3]
	v_mfma_f32_16x16x32_bf16 v[56:59], v[188:191], v[208:211], v[56:59]
	v_mfma_f32_16x16x32_bf16 v[48:51], v[196:199], v[208:211], v[48:51]
	v_mfma_f32_16x16x32_bf16 v[40:43], v[188:191], v[212:215], v[40:43]
	v_mfma_f32_16x16x32_bf16 v[32:35], v[196:199], v[212:215], v[32:35]
	v_mfma_f32_16x16x32_bf16 v[24:27], v[188:191], v[228:231], v[24:27]
	v_mfma_f32_16x16x32_bf16 v[16:19], v[196:199], v[228:231], v[16:19]
	v_mfma_f32_16x16x32_bf16 v[8:11], v[188:191], v[232:235], v[8:11]
	v_mfma_f32_16x16x32_bf16 v[0:3], v[196:199], v[232:235], v[0:3]
	s_setprio 0
	s_barrier
	s_add_i32 s88, s88, 2
	s_add_u32 s4, s4, 0x100
	s_addc_u32 s5, s5, 0
	s_add_u32 s86, s86, 0x100
	s_addc_u32 s87, s87, 0
	s_cmp_gt_u32 s88, 29
	s_cbranch_scc0 .LBB0_109
	s_and_b64 vcc, exec, s[52:53]
	s_cbranch_vccz .LBB0_112
	s_barrier

.LBB0_547:
	ds_read_b128 v[168:171], v151
	ds_read_b128 v[172:175], v152
	ds_read_b128 v[176:179], v153
	ds_read_b128 v[180:183], v154
	ds_read_b128 v[184:187], v155
	ds_read_b128 v[188:191], v156
	ds_read_b128 v[192:195], v157
	ds_read_b128 v[196:199], v158
	s_add_u32 s26, s4, 0xfff80080
	s_addc_u32 s27, s5, -1
	s_cmp_eq_u32 s84, 28
	s_cselect_b32 s57, s35, s27
	s_cselect_b32 s56, s80, s26
	s_cselect_b32 s55, s47, s83
	s_cselect_b32 s54, s81, s82
	s_add_i32 m0, s62, 0xc000
	ds_read_b128 v[200:203], v159
	ds_read_b128 v[204:207], v159 offset:2048
	ds_read_b128 v[208:211], v160
	ds_read_b128 v[212:215], v160 offset:2048
	ds_read_b128 v[216:219], v159 offset:4096
	ds_read_b128 v[220:223], v159 offset:6144
	ds_read_b128 v[228:231], v160 offset:4096
	ds_read_b128 v[232:235], v160 offset:6144
	global_load_lds_dwordx4 v136, s[4:5]
	s_add_i32 m0, s62, 0xe000
	s_nop 0
	global_load_lds_dwordx4 v138, s[4:5]
	s_waitcnt vmcnt(8)
	s_waitcnt lgkmcnt(0)
	s_barrier
	s_setprio 1
	s_waitcnt lgkmcnt(0)
	v_mfma_f32_16x16x32_bf16 v[124:127], v[168:171], v[200:203], v[124:127]
	v_mfma_f32_16x16x32_bf16 v[116:119], v[176:179], v[200:203], v[116:119]
	v_mfma_f32_16x16x32_bf16 v[108:111], v[168:171], v[204:207], v[108:111]
	v_mfma_f32_16x16x32_bf16 v[100:103], v[176:179], v[204:207], v[100:103]
	v_mfma_f32_16x16x32_bf16 v[92:95], v[168:171], v[216:219], v[92:95]
	v_mfma_f32_16x16x32_bf16 v[84:87], v[176:179], v[216:219], v[84:87]
	v_mfma_f32_16x16x32_bf16 v[76:79], v[168:171], v[220:223], v[76:79]
	v_mfma_f32_16x16x32_bf16 v[68:71], v[176:179], v[220:223], v[68:71]
	v_mfma_f32_16x16x32_bf16 v[124:127], v[172:175], v[208:211], v[124:127]
	v_mfma_f32_16x16x32_bf16 v[116:119], v[180:183], v[208:211], v[116:119]
	v_mfma_f32_16x16x32_bf16 v[108:111], v[172:175], v[212:215], v[108:111]
	v_mfma_f32_16x16x32_bf16 v[100:103], v[180:183], v[212:215], v[100:103]
	v_mfma_f32_16x16x32_bf16 v[92:95], v[172:175], v[228:231], v[92:95]
	v_mfma_f32_16x16x32_bf16 v[84:87], v[180:183], v[228:231], v[84:87]
	v_mfma_f32_16x16x32_bf16 v[76:79], v[172:175], v[232:235], v[76:79]
	v_mfma_f32_16x16x32_bf16 v[68:71], v[180:183], v[232:235], v[68:71]
	s_setprio 0
	s_setprio 1
	v_mfma_f32_16x16x32_bf16 v[120:123], v[184:187], v[200:203], v[120:123]
	v_mfma_f32_16x16x32_bf16 v[112:115], v[192:195], v[200:203], v[112:115]
	v_mfma_f32_16x16x32_bf16 v[104:107], v[184:187], v[204:207], v[104:107]
	v_mfma_f32_16x16x32_bf16 v[96:99], v[192:195], v[204:207], v[96:99]
	v_mfma_f32_16x16x32_bf16 v[88:91], v[184:187], v[216:219], v[88:91]
	v_mfma_f32_16x16x32_bf16 v[80:83], v[192:195], v[216:219], v[80:83]
	v_mfma_f32_16x16x32_bf16 v[72:75], v[184:187], v[220:223], v[72:75]
	v_mfma_f32_16x16x32_bf16 v[64:67], v[192:195], v[220:223], v[64:67]
	v_mfma_f32_16x16x32_bf16 v[120:123], v[188:191], v[208:211], v[120:123]
	v_mfma_f32_16x16x32_bf16 v[112:115], v[196:199], v[208:211], v[112:115]
	v_mfma_f32_16x16x32_bf16 v[104:107], v[188:191], v[212:215], v[104:107]
	v_mfma_f32_16x16x32_bf16 v[96:99], v[196:199], v[212:215], v[96:99]
	v_mfma_f32_16x16x32_bf16 v[88:91], v[188:191], v[228:231], v[88:91]
	v_mfma_f32_16x16x32_bf16 v[80:83], v[196:199], v[228:231], v[80:83]
	v_mfma_f32_16x16x32_bf16 v[72:75], v[188:191], v[232:235], v[72:75]
	v_mfma_f32_16x16x32_bf16 v[64:67], v[196:199], v[232:235], v[64:67]
	s_setprio 0
	s_barrier
	s_add_i32 s26, s71, s60
	s_mov_b32 m0, s26
	ds_read_b128 v[200:203], v159 offset:16384
	ds_read_b128 v[204:207], v159 offset:18432
	ds_read_b128 v[208:211], v160 offset:16384
	ds_read_b128 v[212:215], v160 offset:18432
	ds_read_b128 v[216:219], v159 offset:20480
	ds_read_b128 v[220:223], v159 offset:22528
	ds_read_b128 v[228:231], v160 offset:20480
	ds_read_b128 v[232:235], v160 offset:22528
	global_load_lds_dwordx4 v132, s[54:55]
	s_add_i32 m0, s26, 0x2000
	s_add_u32 s86, s54, 0x80000
	s_addc_u32 s87, s55, 0
	s_add_i32 s26, s72, s60
	global_load_lds_dwordx4 v128, s[54:55]
	s_mov_b32 m0, s26
	s_nop 0
	global_load_lds_dwordx4 v132, s[86:87]
	s_add_i32 m0, s26, 0x2000
	s_nop 0
	global_load_lds_dwordx4 v128, s[86:87]
	s_mov_b32 m0, s62
	s_nop 0
	global_load_lds_dwordx4 v134, s[56:57]
	s_mov_b32 m0, s63
	s_nop 0
	global_load_lds_dwordx4 v130, s[56:57]
	s_waitcnt vmcnt(8)
	s_waitcnt lgkmcnt(0)
	s_barrier
	s_setprio 1
	s_waitcnt lgkmcnt(0)
	v_mfma_f32_16x16x32_bf16 v[60:63], v[168:171], v[200:203], v[60:63]
	v_mfma_f32_16x16x32_bf16 v[52:55], v[176:179], v[200:203], v[52:55]
	v_mfma_f32_16x16x32_bf16 v[44:47], v[168:171], v[204:207], v[44:47]
	v_mfma_f32_16x16x32_bf16 v[36:39], v[176:179], v[204:207], v[36:39]
	v_mfma_f32_16x16x32_bf16 v[28:31], v[168:171], v[216:219], v[28:31]
	v_mfma_f32_16x16x32_bf16 v[20:23], v[176:179], v[216:219], v[20:23]
	v_mfma_f32_16x16x32_bf16 v[12:15], v[168:171], v[220:223], v[12:15]
	v_mfma_f32_16x16x32_bf16 v[4:7], v[176:179], v[220:223], v[4:7]
	v_mfma_f32_16x16x32_bf16 v[60:63], v[172:175], v[208:211], v[60:63]
	v_mfma_f32_16x16x32_bf16 v[52:55], v[180:183], v[208:211], v[52:55]
	v_mfma_f32_16x16x32_bf16 v[44:47], v[172:175], v[212:215], v[44:47]
	v_mfma_f32_16x16x32_bf16 v[36:39], v[180:183], v[212:215], v[36:39]
	v_mfma_f32_16x16x32_bf16 v[28:31], v[172:175], v[228:231], v[28:31]
	v_mfma_f32_16x16x32_bf16 v[20:23], v[180:183], v[228:231], v[20:23]
	v_mfma_f32_16x16x32_bf16 v[12:15], v[172:175], v[232:235], v[12:15]
	v_mfma_f32_16x16x32_bf16 v[4:7], v[180:183], v[232:235], v[4:7]
	s_setprio 0
	s_setprio 1
	v_mfma_f32_16x16x32_bf16 v[56:59], v[184:187], v[200:203], v[56:59]
	v_mfma_f32_16x16x32_bf16 v[48:51], v[192:195], v[200:203], v[48:51]
	v_mfma_f32_16x16x32_bf16 v[40:43], v[184:187], v[204:207], v[40:43]
	v_mfma_f32_16x16x32_bf16 v[32:35], v[192:195], v[204:207], v[32:35]
	v_mfma_f32_16x16x32_bf16 v[24:27], v[184:187], v[216:219], v[24:27]
	v_mfma_f32_16x16x32_bf16 v[16:19], v[192:195], v[216:219], v[16:19]
	v_mfma_f32_16x16x32_bf16 v[8:11], v[184:187], v[220:223], v[8:11]
	v_mfma_f32_16x16x32_bf16 v[0:3], v[192:195], v[220:223], v[0:3]
	v_mfma_f32_16x16x32_bf16 v[56:59], v[188:191], v[208:211], v[56:59]
	v_mfma_f32_16x16x32_bf16 v[48:51], v[196:199], v[208:211], v[48:51]
	v_mfma_f32_16x16x32_bf16 v[40:43], v[188:191], v[212:215], v[40:43]
	v_mfma_f32_16x16x32_bf16 v[32:35], v[196:199], v[212:215], v[32:35]
	v_mfma_f32_16x16x32_bf16 v[24:27], v[188:191], v[228:231], v[24:27]
	v_mfma_f32_16x16x32_bf16 v[16:19], v[196:199], v[228:231], v[16:19]
	v_mfma_f32_16x16x32_bf16 v[8:11], v[188:191], v[232:235], v[8:11]
	v_mfma_f32_16x16x32_bf16 v[0:3], v[196:199], v[232:235], v[0:3]
	s_setprio 0
	s_barrier
	s_add_i32 s26, 0, 0x18000
	v_add_u32_e32 v167, s26, v146
	v_add_u32_e32 v172, s26, v147
	s_add_i32 s27, 0, 0x1c000
	ds_read_b128 v[168:171], v167
	ds_read_b128 v[172:175], v172
	ds_read_b128 v[176:179], v161
	ds_read_b128 v[180:183], v162
	v_add_u32_e32 v167, s27, v146
	v_add_u32_e32 v188, s27, v147
	ds_read_b128 v[184:187], v167
	ds_read_b128 v[188:191], v188
	ds_read_b128 v[192:195], v163
	ds_read_b128 v[196:199], v164
	s_add_u32 s56, s56, 0x80000
	s_addc_u32 s57, s57, 0
	s_mov_b32 m0, s64
	ds_read_b128 v[200:203], v159 offset:32768
	ds_read_b128 v[204:207], v159 offset:34816
	ds_read_b128 v[208:211], v160 offset:32768
	ds_read_b128 v[212:215], v160 offset:34816
	ds_read_b128 v[216:219], v159 offset:36864
	ds_read_b128 v[220:223], v159 offset:38912
	ds_read_b128 v[228:231], v160 offset:36864
	ds_read_b128 v[232:235], v160 offset:38912
	global_load_lds_dwordx4 v134, s[56:57]
	s_mov_b32 m0, s65
	s_nop 0
	global_load_lds_dwordx4 v130, s[56:57]
	s_waitcnt vmcnt(8)
	s_waitcnt lgkmcnt(0)
	s_barrier
	s_setprio 1
	s_waitcnt lgkmcnt(0)
	v_mfma_f32_16x16x32_bf16 v[124:127], v[168:171], v[200:203], v[124:127]
	v_mfma_f32_16x16x32_bf16 v[116:119], v[176:179], v[200:203], v[116:119]
	v_mfma_f32_16x16x32_bf16 v[108:111], v[168:171], v[204:207], v[108:111]
	v_mfma_f32_16x16x32_bf16 v[100:103], v[176:179], v[204:207], v[100:103]
	v_mfma_f32_16x16x32_bf16 v[92:95], v[168:171], v[216:219], v[92:95]
	v_mfma_f32_16x16x32_bf16 v[84:87], v[176:179], v[216:219], v[84:87]
	v_mfma_f32_16x16x32_bf16 v[76:79], v[168:171], v[220:223], v[76:79]
	v_mfma_f32_16x16x32_bf16 v[68:71], v[176:179], v[220:223], v[68:71]
	v_mfma_f32_16x16x32_bf16 v[124:127], v[172:175], v[208:211], v[124:127]
	v_mfma_f32_16x16x32_bf16 v[116:119], v[180:183], v[208:211], v[116:119]
	v_mfma_f32_16x16x32_bf16 v[108:111], v[172:175], v[212:215], v[108:111]
	v_mfma_f32_16x16x32_bf16 v[100:103], v[180:183], v[212:215], v[100:103]
	v_mfma_f32_16x16x32_bf16 v[92:95], v[172:175], v[228:231], v[92:95]
	v_mfma_f32_16x16x32_bf16 v[84:87], v[180:183], v[228:231], v[84:87]
	v_mfma_f32_16x16x32_bf16 v[76:79], v[172:175], v[232:235], v[76:79]
	v_mfma_f32_16x16x32_bf16 v[68:71], v[180:183], v[232:235], v[68:71]
	s_setprio 0
	s_setprio 1
	v_mfma_f32_16x16x32_bf16 v[120:123], v[184:187], v[200:203], v[120:123]
	v_mfma_f32_16x16x32_bf16 v[112:115], v[192:195], v[200:203], v[112:115]
	v_mfma_f32_16x16x32_bf16 v[104:107], v[184:187], v[204:207], v[104:107]
	v_mfma_f32_16x16x32_bf16 v[96:99], v[192:195], v[204:207], v[96:99]
	v_mfma_f32_16x16x32_bf16 v[88:91], v[184:187], v[216:219], v[88:91]
	v_mfma_f32_16x16x32_bf16 v[80:83], v[192:195], v[216:219], v[80:83]
	v_mfma_f32_16x16x32_bf16 v[72:75], v[184:187], v[220:223], v[72:75]
	v_mfma_f32_16x16x32_bf16 v[64:67], v[192:195], v[220:223], v[64:67]
	v_mfma_f32_16x16x32_bf16 v[120:123], v[188:191], v[208:211], v[120:123]
	v_mfma_f32_16x16x32_bf16 v[112:115], v[196:199], v[208:211], v[112:115]
	v_mfma_f32_16x16x32_bf16 v[104:107], v[188:191], v[212:215], v[104:107]
	v_mfma_f32_16x16x32_bf16 v[96:99], v[196:199], v[212:215], v[96:99]
	v_mfma_f32_16x16x32_bf16 v[88:91], v[188:191], v[228:231], v[88:91]
	v_mfma_f32_16x16x32_bf16 v[80:83], v[196:199], v[228:231], v[80:83]
	v_mfma_f32_16x16x32_bf16 v[72:75], v[188:191], v[232:235], v[72:75]
	v_mfma_f32_16x16x32_bf16 v[64:67], v[196:199], v[232:235], v[64:67]
	s_setprio 0
	s_barrier
	s_add_i32 s26, s26, s60
	s_add_i32 m0, s26, 0xffffff80
	ds_read_b128 v[200:203], v159 offset:49152
	ds_read_b128 v[204:207], v159 offset:51200
	ds_read_b128 v[208:211], v160 offset:49152
	ds_read_b128 v[212:215], v160 offset:51200
	ds_read_b128 v[216:219], v159 offset:53248
	ds_read_b128 v[220:223], v159 offset:55296
	ds_read_b128 v[228:231], v160 offset:53248
	ds_read_b128 v[232:235], v160 offset:55296
	global_load_lds_dwordx4 v132, s[54:55] offset:128
	s_add_i32 m0, s26, 0x1f80
	s_add_i32 s26, s27, s60
	global_load_lds_dwordx4 v128, s[54:55] offset:128
	s_add_u32 s54, s54, 0x80080
	s_addc_u32 s55, s55, 0
	s_mov_b32 m0, s26
	s_nop 0
	global_load_lds_dwordx4 v132, s[54:55]
	s_add_i32 m0, s26, 0x2000
	s_nop 0
	global_load_lds_dwordx4 v128, s[54:55]
	s_add_u32 s86, s56, 0xfff80080
	s_addc_u32 s87, s57, -1
	s_mov_b32 m0, s67
	s_nop 0
	global_load_lds_dwordx4 v134, s[86:87]
	s_mov_b32 m0, s68
	s_nop 0
	global_load_lds_dwordx4 v130, s[86:87]
	s_waitcnt vmcnt(8)
	s_waitcnt lgkmcnt(0)
	s_barrier
	s_setprio 1
	s_waitcnt lgkmcnt(0)
	v_mfma_f32_16x16x32_bf16 v[60:63], v[168:171], v[200:203], v[60:63]
	v_mfma_f32_16x16x32_bf16 v[52:55], v[176:179], v[200:203], v[52:55]
	v_mfma_f32_16x16x32_bf16 v[44:47], v[168:171], v[204:207], v[44:47]
	v_mfma_f32_16x16x32_bf16 v[36:39], v[176:179], v[204:207], v[36:39]
	v_mfma_f32_16x16x32_bf16 v[28:31], v[168:171], v[216:219], v[28:31]
	v_mfma_f32_16x16x32_bf16 v[20:23], v[176:179], v[216:219], v[20:23]
	v_mfma_f32_16x16x32_bf16 v[12:15], v[168:171], v[220:223], v[12:15]
	v_mfma_f32_16x16x32_bf16 v[4:7], v[176:179], v[220:223], v[4:7]
	v_mfma_f32_16x16x32_bf16 v[60:63], v[172:175], v[208:211], v[60:63]
	v_mfma_f32_16x16x32_bf16 v[52:55], v[180:183], v[208:211], v[52:55]
	v_mfma_f32_16x16x32_bf16 v[44:47], v[172:175], v[212:215], v[44:47]
	v_mfma_f32_16x16x32_bf16 v[36:39], v[180:183], v[212:215], v[36:39]
	v_mfma_f32_16x16x32_bf16 v[28:31], v[172:175], v[228:231], v[28:31]
	v_mfma_f32_16x16x32_bf16 v[20:23], v[180:183], v[228:231], v[20:23]
	v_mfma_f32_16x16x32_bf16 v[12:15], v[172:175], v[232:235], v[12:15]
	v_mfma_f32_16x16x32_bf16 v[4:7], v[180:183], v[232:235], v[4:7]
	s_setprio 0
	s_setprio 1
	v_mfma_f32_16x16x32_bf16 v[56:59], v[184:187], v[200:203], v[56:59]
	v_mfma_f32_16x16x32_bf16 v[48:51], v[192:195], v[200:203], v[48:51]
	v_mfma_f32_16x16x32_bf16 v[40:43], v[184:187], v[204:207], v[40:43]
	v_mfma_f32_16x16x32_bf16 v[32:35], v[192:195], v[204:207], v[32:35]
	v_mfma_f32_16x16x32_bf16 v[24:27], v[184:187], v[216:219], v[24:27]
	v_mfma_f32_16x16x32_bf16 v[16:19], v[192:195], v[216:219], v[16:19]
	v_mfma_f32_16x16x32_bf16 v[8:11], v[184:187], v[220:223], v[8:11]
	v_mfma_f32_16x16x32_bf16 v[0:3], v[192:195], v[220:223], v[0:3]
	v_mfma_f32_16x16x32_bf16 v[56:59], v[188:191], v[208:211], v[56:59]
	v_mfma_f32_16x16x32_bf16 v[48:51], v[196:199], v[208:211], v[48:51]
	v_mfma_f32_16x16x32_bf16 v[40:43], v[188:191], v[212:215], v[40:43]
	v_mfma_f32_16x16x32_bf16 v[32:35], v[196:199], v[212:215], v[32:35]
	v_mfma_f32_16x16x32_bf16 v[24:27], v[188:191], v[228:231], v[24:27]
	v_mfma_f32_16x16x32_bf16 v[16:19], v[196:199], v[228:231], v[16:19]
	v_mfma_f32_16x16x32_bf16 v[8:11], v[188:191], v[232:235], v[8:11]
	v_mfma_f32_16x16x32_bf16 v[0:3], v[196:199], v[232:235], v[0:3]
	s_setprio 0
	s_barrier
	s_add_i32 s84, s84, 2
	s_add_u32 s4, s4, 0x100
	s_addc_u32 s5, s5, 0
	s_add_u32 s82, s82, 0x100
	s_addc_u32 s83, s83, 0
	s_cmp_gt_u32 s84, 29
	s_cbranch_scc0 .LBB0_547
	s_and_b64 vcc, exec, s[42:43]
	s_cbranch_vccz .LBB0_550
	s_barrier

.LBB0_776:
	ds_read_b128 v[176:179], v151
	ds_read_b128 v[180:183], v152
	ds_read_b128 v[184:187], v153
	ds_read_b128 v[188:191], v154
	ds_read_b128 v[192:195], v155
	ds_read_b128 v[196:199], v156
	ds_read_b128 v[200:203], v157
	ds_read_b128 v[204:207], v158
	s_add_u32 s26, s4, 0xfff80080
	s_addc_u32 s27, s5, -1
	s_cmp_eq_u32 vcc_lo, 28
	s_cselect_b32 s65, s37, s27
	s_cselect_b32 s64, s94, s26
	s_cselect_b32 s63, s57, s97
	s_cselect_b32 s62, s95, s96
	s_add_i32 m0, s75, 0xc000
	ds_read_b128 v[208:211], v159
	ds_read_b128 v[212:215], v159 offset:2048
	ds_read_b128 v[216:219], v160
	ds_read_b128 v[220:223], v160 offset:2048
	ds_read_b128 v[228:231], v159 offset:4096
	ds_read_b128 v[232:235], v159 offset:6144
	ds_read_b128 v[236:239], v160 offset:4096
	ds_read_b128 v[240:243], v160 offset:6144
	global_load_lds_dwordx4 v136, s[4:5]
	s_add_i32 m0, s75, 0xe000
	s_nop 0
	global_load_lds_dwordx4 v138, s[4:5]
	s_waitcnt vmcnt(8)
	s_waitcnt lgkmcnt(0)
	s_barrier
	s_setprio 1
	s_waitcnt lgkmcnt(0)
	v_mfma_f32_16x16x32_bf16 v[124:127], v[176:179], v[208:211], v[124:127]
	v_mfma_f32_16x16x32_bf16 v[120:123], v[184:187], v[208:211], v[120:123]
	v_mfma_f32_16x16x32_bf16 v[108:111], v[176:179], v[212:215], v[108:111]
	v_mfma_f32_16x16x32_bf16 v[104:107], v[184:187], v[212:215], v[104:107]
	v_mfma_f32_16x16x32_bf16 v[92:95], v[176:179], v[228:231], v[92:95]
	v_mfma_f32_16x16x32_bf16 v[88:91], v[184:187], v[228:231], v[88:91]
	v_mfma_f32_16x16x32_bf16 v[76:79], v[176:179], v[232:235], v[76:79]
	v_mfma_f32_16x16x32_bf16 v[72:75], v[184:187], v[232:235], v[72:75]
	v_mfma_f32_16x16x32_bf16 v[124:127], v[180:183], v[216:219], v[124:127]
	v_mfma_f32_16x16x32_bf16 v[120:123], v[188:191], v[216:219], v[120:123]
	v_mfma_f32_16x16x32_bf16 v[108:111], v[180:183], v[220:223], v[108:111]
	v_mfma_f32_16x16x32_bf16 v[104:107], v[188:191], v[220:223], v[104:107]
	v_mfma_f32_16x16x32_bf16 v[92:95], v[180:183], v[236:239], v[92:95]
	v_mfma_f32_16x16x32_bf16 v[88:91], v[188:191], v[236:239], v[88:91]
	v_mfma_f32_16x16x32_bf16 v[76:79], v[180:183], v[240:243], v[76:79]
	v_mfma_f32_16x16x32_bf16 v[72:75], v[188:191], v[240:243], v[72:75]
	s_setprio 0
	s_setprio 1
	v_mfma_f32_16x16x32_bf16 v[116:119], v[192:195], v[208:211], v[116:119]
	v_mfma_f32_16x16x32_bf16 v[112:115], v[200:203], v[208:211], v[112:115]
	v_mfma_f32_16x16x32_bf16 v[100:103], v[192:195], v[212:215], v[100:103]
	v_mfma_f32_16x16x32_bf16 v[96:99], v[200:203], v[212:215], v[96:99]
	v_mfma_f32_16x16x32_bf16 v[84:87], v[192:195], v[228:231], v[84:87]
	v_mfma_f32_16x16x32_bf16 v[80:83], v[200:203], v[228:231], v[80:83]
	v_mfma_f32_16x16x32_bf16 v[68:71], v[192:195], v[232:235], v[68:71]
	v_mfma_f32_16x16x32_bf16 v[64:67], v[200:203], v[232:235], v[64:67]
	v_mfma_f32_16x16x32_bf16 v[116:119], v[196:199], v[216:219], v[116:119]
	v_mfma_f32_16x16x32_bf16 v[112:115], v[204:207], v[216:219], v[112:115]
	v_mfma_f32_16x16x32_bf16 v[100:103], v[196:199], v[220:223], v[100:103]
	v_mfma_f32_16x16x32_bf16 v[96:99], v[204:207], v[220:223], v[96:99]
	v_mfma_f32_16x16x32_bf16 v[84:87], v[196:199], v[236:239], v[84:87]
	v_mfma_f32_16x16x32_bf16 v[80:83], v[204:207], v[236:239], v[80:83]
	v_mfma_f32_16x16x32_bf16 v[68:71], v[196:199], v[240:243], v[68:71]
	v_mfma_f32_16x16x32_bf16 v[64:67], v[204:207], v[240:243], v[64:67]
	s_setprio 0
	s_barrier
	s_add_i32 s26, s84, s74
	s_mov_b32 m0, s26
	ds_read_b128 v[208:211], v159 offset:16384
	ds_read_b128 v[212:215], v159 offset:18432
	ds_read_b128 v[216:219], v160 offset:16384
	ds_read_b128 v[220:223], v160 offset:18432
	ds_read_b128 v[228:231], v159 offset:20480
	ds_read_b128 v[232:235], v159 offset:22528
	ds_read_b128 v[236:239], v160 offset:20480
	ds_read_b128 v[240:243], v160 offset:22528
	global_load_lds_dwordx4 v132, s[62:63]
	s_add_i32 m0, s26, 0x2000
	s_add_u32 s26, s62, 0x80000
	s_addc_u32 s27, s63, 0
	s_add_i32 vcc_hi, s85, s74
	global_load_lds_dwordx4 v128, s[62:63]
	s_mov_b32 m0, vcc_hi
	s_nop 0
	global_load_lds_dwordx4 v132, s[26:27]
	s_add_i32 m0, vcc_hi, 0x2000
	s_nop 0
	global_load_lds_dwordx4 v128, s[26:27]
	s_mov_b32 m0, s75
	s_nop 0
	global_load_lds_dwordx4 v134, s[64:65]
	s_mov_b32 m0, s78
	s_nop 0
	global_load_lds_dwordx4 v130, s[64:65]
	s_waitcnt vmcnt(8)
	s_waitcnt lgkmcnt(0)
	s_barrier
	s_setprio 1
	s_waitcnt lgkmcnt(0)
	v_mfma_f32_16x16x32_bf16 v[60:63], v[176:179], v[208:211], v[60:63]
	v_mfma_f32_16x16x32_bf16 v[56:59], v[184:187], v[208:211], v[56:59]
	v_mfma_f32_16x16x32_bf16 v[48:51], v[176:179], v[212:215], v[48:51]
	v_mfma_f32_16x16x32_bf16 v[40:43], v[184:187], v[212:215], v[40:43]
	v_mfma_f32_16x16x32_bf16 v[32:35], v[176:179], v[228:231], v[32:35]
	v_mfma_f32_16x16x32_bf16 v[24:27], v[184:187], v[228:231], v[24:27]
	v_mfma_f32_16x16x32_bf16 v[16:19], v[176:179], v[232:235], v[16:19]
	v_mfma_f32_16x16x32_bf16 v[8:11], v[184:187], v[232:235], v[8:11]
	v_mfma_f32_16x16x32_bf16 v[60:63], v[180:183], v[216:219], v[60:63]
	v_mfma_f32_16x16x32_bf16 v[56:59], v[188:191], v[216:219], v[56:59]
	v_mfma_f32_16x16x32_bf16 v[48:51], v[180:183], v[220:223], v[48:51]
	v_mfma_f32_16x16x32_bf16 v[40:43], v[188:191], v[220:223], v[40:43]
	v_mfma_f32_16x16x32_bf16 v[32:35], v[180:183], v[236:239], v[32:35]
	v_mfma_f32_16x16x32_bf16 v[24:27], v[188:191], v[236:239], v[24:27]
	v_mfma_f32_16x16x32_bf16 v[16:19], v[180:183], v[240:243], v[16:19]
	v_mfma_f32_16x16x32_bf16 v[8:11], v[188:191], v[240:243], v[8:11]
	s_setprio 0
	s_setprio 1
	v_mfma_f32_16x16x32_bf16 v[52:55], v[192:195], v[208:211], v[52:55]
	v_mfma_f32_16x16x32_bf16 v[44:47], v[200:203], v[208:211], v[44:47]
	v_mfma_f32_16x16x32_bf16 v[36:39], v[192:195], v[212:215], v[36:39]
	v_mfma_f32_16x16x32_bf16 v[28:31], v[200:203], v[212:215], v[28:31]
	v_mfma_f32_16x16x32_bf16 v[20:23], v[192:195], v[228:231], v[20:23]
	v_mfma_f32_16x16x32_bf16 v[12:15], v[200:203], v[228:231], v[12:15]
	v_mfma_f32_16x16x32_bf16 v[4:7], v[192:195], v[232:235], v[4:7]
	v_mfma_f32_16x16x32_bf16 v[0:3], v[200:203], v[232:235], v[0:3]
	v_mfma_f32_16x16x32_bf16 v[52:55], v[196:199], v[216:219], v[52:55]
	v_mfma_f32_16x16x32_bf16 v[44:47], v[204:207], v[216:219], v[44:47]
	v_mfma_f32_16x16x32_bf16 v[36:39], v[196:199], v[220:223], v[36:39]
	v_mfma_f32_16x16x32_bf16 v[28:31], v[204:207], v[220:223], v[28:31]
	v_mfma_f32_16x16x32_bf16 v[20:23], v[196:199], v[236:239], v[20:23]
	v_mfma_f32_16x16x32_bf16 v[12:15], v[204:207], v[236:239], v[12:15]
	v_mfma_f32_16x16x32_bf16 v[4:7], v[196:199], v[240:243], v[4:7]
	v_mfma_f32_16x16x32_bf16 v[0:3], v[204:207], v[240:243], v[0:3]
	s_setprio 0
	s_barrier
	s_add_i32 vcc_hi, 0, 0x18000
	s_add_i32 s7, 0, 0x1c000
	v_add_u32_e32 v176, vcc_hi, v146
	v_add_u32_e32 v180, vcc_hi, v147
	v_add_u32_e32 v192, s7, v146
	v_add_u32_e32 v196, s7, v147
	ds_read_b128 v[176:179], v176
	ds_read_b128 v[180:183], v180
	ds_read_b128 v[184:187], v161
	ds_read_b128 v[188:191], v171
	ds_read_b128 v[192:195], v192
	ds_read_b128 v[196:199], v196
	ds_read_b128 v[200:203], v172
	ds_read_b128 v[204:207], v173
	s_add_u32 s26, s64, 0x80000
	s_addc_u32 s27, s65, 0
	s_mov_b32 m0, s79
	ds_read_b128 v[208:211], v159 offset:32768
	ds_read_b128 v[212:215], v159 offset:34816
	ds_read_b128 v[216:219], v160 offset:32768
	ds_read_b128 v[220:223], v160 offset:34816
	ds_read_b128 v[228:231], v159 offset:36864
	ds_read_b128 v[232:235], v159 offset:38912
	ds_read_b128 v[236:239], v160 offset:36864
	ds_read_b128 v[240:243], v160 offset:38912
	global_load_lds_dwordx4 v134, s[26:27]
	s_mov_b32 m0, s80
	s_nop 0
	global_load_lds_dwordx4 v130, s[26:27]
	s_waitcnt vmcnt(8)
	s_waitcnt lgkmcnt(0)
	s_barrier
	s_setprio 1
	s_waitcnt lgkmcnt(0)
	v_mfma_f32_16x16x32_bf16 v[124:127], v[176:179], v[208:211], v[124:127]
	v_mfma_f32_16x16x32_bf16 v[120:123], v[184:187], v[208:211], v[120:123]
	v_mfma_f32_16x16x32_bf16 v[108:111], v[176:179], v[212:215], v[108:111]
	v_mfma_f32_16x16x32_bf16 v[104:107], v[184:187], v[212:215], v[104:107]
	v_mfma_f32_16x16x32_bf16 v[92:95], v[176:179], v[228:231], v[92:95]
	v_mfma_f32_16x16x32_bf16 v[88:91], v[184:187], v[228:231], v[88:91]
	v_mfma_f32_16x16x32_bf16 v[76:79], v[176:179], v[232:235], v[76:79]
	v_mfma_f32_16x16x32_bf16 v[72:75], v[184:187], v[232:235], v[72:75]
	v_mfma_f32_16x16x32_bf16 v[124:127], v[180:183], v[216:219], v[124:127]
	v_mfma_f32_16x16x32_bf16 v[120:123], v[188:191], v[216:219], v[120:123]
	v_mfma_f32_16x16x32_bf16 v[108:111], v[180:183], v[220:223], v[108:111]
	v_mfma_f32_16x16x32_bf16 v[104:107], v[188:191], v[220:223], v[104:107]
	v_mfma_f32_16x16x32_bf16 v[92:95], v[180:183], v[236:239], v[92:95]
	v_mfma_f32_16x16x32_bf16 v[88:91], v[188:191], v[236:239], v[88:91]
	v_mfma_f32_16x16x32_bf16 v[76:79], v[180:183], v[240:243], v[76:79]
	v_mfma_f32_16x16x32_bf16 v[72:75], v[188:191], v[240:243], v[72:75]
	s_setprio 0
	s_setprio 1
	v_mfma_f32_16x16x32_bf16 v[116:119], v[192:195], v[208:211], v[116:119]
	v_mfma_f32_16x16x32_bf16 v[112:115], v[200:203], v[208:211], v[112:115]
	v_mfma_f32_16x16x32_bf16 v[100:103], v[192:195], v[212:215], v[100:103]
	v_mfma_f32_16x16x32_bf16 v[96:99], v[200:203], v[212:215], v[96:99]
	v_mfma_f32_16x16x32_bf16 v[84:87], v[192:195], v[228:231], v[84:87]
	v_mfma_f32_16x16x32_bf16 v[80:83], v[200:203], v[228:231], v[80:83]
	v_mfma_f32_16x16x32_bf16 v[68:71], v[192:195], v[232:235], v[68:71]
	v_mfma_f32_16x16x32_bf16 v[64:67], v[200:203], v[232:235], v[64:67]
	v_mfma_f32_16x16x32_bf16 v[116:119], v[196:199], v[216:219], v[116:119]
	v_mfma_f32_16x16x32_bf16 v[112:115], v[204:207], v[216:219], v[112:115]
	v_mfma_f32_16x16x32_bf16 v[100:103], v[196:199], v[220:223], v[100:103]
	v_mfma_f32_16x16x32_bf16 v[96:99], v[204:207], v[220:223], v[96:99]
	v_mfma_f32_16x16x32_bf16 v[84:87], v[196:199], v[236:239], v[84:87]
	v_mfma_f32_16x16x32_bf16 v[80:83], v[204:207], v[236:239], v[80:83]
	v_mfma_f32_16x16x32_bf16 v[68:71], v[196:199], v[240:243], v[68:71]
	v_mfma_f32_16x16x32_bf16 v[64:67], v[204:207], v[240:243], v[64:67]
	s_setprio 0
	s_barrier
	s_add_i32 s26, vcc_hi, s74
	s_add_i32 m0, s26, 0xffffff80
	ds_read_b128 v[208:211], v159 offset:49152
	ds_read_b128 v[212:215], v159 offset:51200
	ds_read_b128 v[216:219], v160 offset:49152
	ds_read_b128 v[220:223], v160 offset:51200
	ds_read_b128 v[228:231], v159 offset:53248
	ds_read_b128 v[232:235], v159 offset:55296
	ds_read_b128 v[236:239], v160 offset:53248
	ds_read_b128 v[240:243], v160 offset:55296
	global_load_lds_dwordx4 v132, s[62:63] offset:128
	s_add_i32 m0, s26, 0x1f80
	s_add_u32 s26, s62, 0x80080
	s_addc_u32 s27, s63, 0
	s_add_i32 s7, s7, s74
	global_load_lds_dwordx4 v128, s[62:63] offset:128
	s_mov_b32 m0, s7
	s_nop 0
	global_load_lds_dwordx4 v132, s[26:27]
	s_add_i32 m0, s7, 0x2000
	s_nop 0
	global_load_lds_dwordx4 v128, s[26:27]
	s_add_i32 m0, s81, 0xffffff80
	s_nop 0
	global_load_lds_dwordx4 v134, s[64:65] offset:128
	s_add_i32 m0, s82, 0xffffff80
	s_nop 0
	global_load_lds_dwordx4 v130, s[64:65] offset:128
	s_waitcnt vmcnt(8)
	s_waitcnt lgkmcnt(0)
	s_barrier
	s_setprio 1
	s_waitcnt lgkmcnt(0)
	v_mfma_f32_16x16x32_bf16 v[60:63], v[176:179], v[208:211], v[60:63]
	v_mfma_f32_16x16x32_bf16 v[56:59], v[184:187], v[208:211], v[56:59]
	v_mfma_f32_16x16x32_bf16 v[48:51], v[176:179], v[212:215], v[48:51]
	v_mfma_f32_16x16x32_bf16 v[40:43], v[184:187], v[212:215], v[40:43]
	v_mfma_f32_16x16x32_bf16 v[32:35], v[176:179], v[228:231], v[32:35]
	v_mfma_f32_16x16x32_bf16 v[24:27], v[184:187], v[228:231], v[24:27]
	v_mfma_f32_16x16x32_bf16 v[16:19], v[176:179], v[232:235], v[16:19]
	v_mfma_f32_16x16x32_bf16 v[8:11], v[184:187], v[232:235], v[8:11]
	v_mfma_f32_16x16x32_bf16 v[60:63], v[180:183], v[216:219], v[60:63]
	v_mfma_f32_16x16x32_bf16 v[56:59], v[188:191], v[216:219], v[56:59]
	v_mfma_f32_16x16x32_bf16 v[48:51], v[180:183], v[220:223], v[48:51]
	v_mfma_f32_16x16x32_bf16 v[40:43], v[188:191], v[220:223], v[40:43]
	v_mfma_f32_16x16x32_bf16 v[32:35], v[180:183], v[236:239], v[32:35]
	v_mfma_f32_16x16x32_bf16 v[24:27], v[188:191], v[236:239], v[24:27]
	v_mfma_f32_16x16x32_bf16 v[16:19], v[180:183], v[240:243], v[16:19]
	v_mfma_f32_16x16x32_bf16 v[8:11], v[188:191], v[240:243], v[8:11]
	s_setprio 0
	s_setprio 1
	v_mfma_f32_16x16x32_bf16 v[52:55], v[192:195], v[208:211], v[52:55]
	v_mfma_f32_16x16x32_bf16 v[44:47], v[200:203], v[208:211], v[44:47]
	v_mfma_f32_16x16x32_bf16 v[36:39], v[192:195], v[212:215], v[36:39]
	v_mfma_f32_16x16x32_bf16 v[28:31], v[200:203], v[212:215], v[28:31]
	v_mfma_f32_16x16x32_bf16 v[20:23], v[192:195], v[228:231], v[20:23]
	v_mfma_f32_16x16x32_bf16 v[12:15], v[200:203], v[228:231], v[12:15]
	v_mfma_f32_16x16x32_bf16 v[4:7], v[192:195], v[232:235], v[4:7]
	v_mfma_f32_16x16x32_bf16 v[0:3], v[200:203], v[232:235], v[0:3]
	v_mfma_f32_16x16x32_bf16 v[52:55], v[196:199], v[216:219], v[52:55]
	v_mfma_f32_16x16x32_bf16 v[44:47], v[204:207], v[216:219], v[44:47]
	v_mfma_f32_16x16x32_bf16 v[36:39], v[196:199], v[220:223], v[36:39]
	v_mfma_f32_16x16x32_bf16 v[28:31], v[204:207], v[220:223], v[28:31]
	v_mfma_f32_16x16x32_bf16 v[20:23], v[196:199], v[236:239], v[20:23]
	v_mfma_f32_16x16x32_bf16 v[12:15], v[204:207], v[236:239], v[12:15]
	v_mfma_f32_16x16x32_bf16 v[4:7], v[196:199], v[240:243], v[4:7]
	v_mfma_f32_16x16x32_bf16 v[0:3], v[204:207], v[240:243], v[0:3]
	s_setprio 0
	s_barrier
	s_add_i32 vcc_lo, vcc_lo, 2
	s_add_u32 s4, s4, 0x100
	s_addc_u32 s5, s5, 0
	s_add_u32 s96, s96, 0x100
	s_addc_u32 s97, s97, 0
	s_cmp_gt_u32 vcc_lo, 29
	s_cbranch_scc0 .LBB0_776
	s_and_b64 vcc, exec, s[48:49]
	s_cbranch_vccz .LBB0_779
	s_barrier

.LBB0_802:
	ds_read_b128 v[128:131], v176
	ds_read_b128 v[132:135], v177
	ds_read_b128 v[136:139], v178
	ds_read_b128 v[140:143], v179
	ds_read_b128 v[192:195], v180
	ds_read_b128 v[196:199], v181
	ds_read_b128 v[200:203], v182
	ds_read_b128 v[204:207], v183
	s_add_u32 s7, s4, 0xfff80080
	s_addc_u32 s26, s5, -1
	s_cmp_eq_u32 s96, 28
	s_cselect_b32 s67, s57, s26
	s_cselect_b32 s66, s92, s7
	s_cselect_b32 s65, s35, s95
	s_cselect_b32 s64, s93, s94
	s_add_i32 m0, s63, 0xc000
	ds_read_b128 v[208:211], v184
	ds_read_b128 v[212:215], v184 offset:2048
	ds_read_b128 v[216:219], v185
	ds_read_b128 v[220:223], v185 offset:2048
	ds_read_b128 v[228:231], v184 offset:4096
	ds_read_b128 v[232:235], v184 offset:6144
	ds_read_b128 v[236:239], v185 offset:4096
	ds_read_b128 v[240:243], v185 offset:6144
	global_load_lds_dwordx4 v152, s[4:5]
	s_add_i32 m0, s63, 0xe000
	s_nop 0
	global_load_lds_dwordx4 v154, s[4:5]
	s_waitcnt vmcnt(8)
	s_waitcnt lgkmcnt(0)
	s_barrier
	s_setprio 1
	s_waitcnt lgkmcnt(0)
	v_mfma_f32_16x16x32_bf16 v[124:127], v[128:131], v[208:211], v[124:127]
	v_mfma_f32_16x16x32_bf16 v[120:123], v[136:139], v[208:211], v[120:123]
	v_mfma_f32_16x16x32_bf16 v[112:115], v[128:131], v[212:215], v[112:115]
	v_mfma_f32_16x16x32_bf16 v[104:107], v[136:139], v[212:215], v[104:107]
	v_mfma_f32_16x16x32_bf16 v[96:99], v[128:131], v[228:231], v[96:99]
	v_mfma_f32_16x16x32_bf16 v[88:91], v[136:139], v[228:231], v[88:91]
	v_mfma_f32_16x16x32_bf16 v[80:83], v[128:131], v[232:235], v[80:83]
	v_mfma_f32_16x16x32_bf16 v[72:75], v[136:139], v[232:235], v[72:75]
	v_mfma_f32_16x16x32_bf16 v[124:127], v[132:135], v[216:219], v[124:127]
	v_mfma_f32_16x16x32_bf16 v[120:123], v[140:143], v[216:219], v[120:123]
	v_mfma_f32_16x16x32_bf16 v[112:115], v[132:135], v[220:223], v[112:115]
	v_mfma_f32_16x16x32_bf16 v[104:107], v[140:143], v[220:223], v[104:107]
	v_mfma_f32_16x16x32_bf16 v[96:99], v[132:135], v[236:239], v[96:99]
	v_mfma_f32_16x16x32_bf16 v[88:91], v[140:143], v[236:239], v[88:91]
	v_mfma_f32_16x16x32_bf16 v[80:83], v[132:135], v[240:243], v[80:83]
	v_mfma_f32_16x16x32_bf16 v[72:75], v[140:143], v[240:243], v[72:75]
	s_setprio 0
	s_setprio 1
	v_mfma_f32_16x16x32_bf16 v[116:119], v[192:195], v[208:211], v[116:119]
	v_mfma_f32_16x16x32_bf16 v[108:111], v[200:203], v[208:211], v[108:111]
	v_mfma_f32_16x16x32_bf16 v[100:103], v[192:195], v[212:215], v[100:103]
	v_mfma_f32_16x16x32_bf16 v[92:95], v[200:203], v[212:215], v[92:95]
	v_mfma_f32_16x16x32_bf16 v[84:87], v[192:195], v[228:231], v[84:87]
	v_mfma_f32_16x16x32_bf16 v[76:79], v[200:203], v[228:231], v[76:79]
	v_mfma_f32_16x16x32_bf16 v[68:71], v[192:195], v[232:235], v[68:71]
	v_mfma_f32_16x16x32_bf16 v[64:67], v[200:203], v[232:235], v[64:67]
	v_mfma_f32_16x16x32_bf16 v[116:119], v[196:199], v[216:219], v[116:119]
	v_mfma_f32_16x16x32_bf16 v[108:111], v[204:207], v[216:219], v[108:111]
	v_mfma_f32_16x16x32_bf16 v[100:103], v[196:199], v[220:223], v[100:103]
	v_mfma_f32_16x16x32_bf16 v[92:95], v[204:207], v[220:223], v[92:95]
	v_mfma_f32_16x16x32_bf16 v[84:87], v[196:199], v[236:239], v[84:87]
	v_mfma_f32_16x16x32_bf16 v[76:79], v[204:207], v[236:239], v[76:79]
	v_mfma_f32_16x16x32_bf16 v[68:71], v[196:199], v[240:243], v[68:71]
	v_mfma_f32_16x16x32_bf16 v[64:67], v[204:207], v[240:243], v[64:67]
	s_setprio 0
	s_barrier
	s_add_i32 s7, s83, s72
	s_mov_b32 m0, s7
	ds_read_b128 v[208:211], v184 offset:16384
	ds_read_b128 v[212:215], v184 offset:18432
	ds_read_b128 v[216:219], v185 offset:16384
	ds_read_b128 v[220:223], v185 offset:18432
	ds_read_b128 v[228:231], v184 offset:20480
	ds_read_b128 v[232:235], v184 offset:22528
	ds_read_b128 v[236:239], v185 offset:20480
	ds_read_b128 v[240:243], v185 offset:22528
	global_load_lds_dwordx4 v148, s[64:65]
	s_add_i32 m0, s7, 0x2000
	s_add_u32 s26, s64, 0x80000
	s_addc_u32 s27, s65, 0
	s_add_i32 s7, s84, s72
	global_load_lds_dwordx4 v144, s[64:65]
	s_mov_b32 m0, s7
	s_nop 0
	global_load_lds_dwordx4 v148, s[26:27]
	s_add_i32 m0, s7, 0x2000
	s_nop 0
	global_load_lds_dwordx4 v144, s[26:27]
	s_mov_b32 m0, s63
	s_nop 0
	global_load_lds_dwordx4 v150, s[66:67]
	s_mov_b32 m0, s75
	s_nop 0
	global_load_lds_dwordx4 v146, s[66:67]
	s_waitcnt vmcnt(8)
	s_waitcnt lgkmcnt(0)
	s_barrier
	s_setprio 1
	s_waitcnt lgkmcnt(0)
	v_mfma_f32_16x16x32_bf16 v[60:63], v[128:131], v[208:211], v[60:63]
	v_mfma_f32_16x16x32_bf16 v[56:59], v[136:139], v[208:211], v[56:59]
	v_mfma_f32_16x16x32_bf16 v[48:51], v[128:131], v[212:215], v[48:51]
	v_mfma_f32_16x16x32_bf16 v[40:43], v[136:139], v[212:215], v[40:43]
	v_mfma_f32_16x16x32_bf16 v[32:35], v[128:131], v[228:231], v[32:35]
	v_mfma_f32_16x16x32_bf16 v[24:27], v[136:139], v[228:231], v[24:27]
	v_mfma_f32_16x16x32_bf16 v[16:19], v[128:131], v[232:235], v[16:19]
	v_mfma_f32_16x16x32_bf16 v[8:11], v[136:139], v[232:235], v[8:11]
	v_mfma_f32_16x16x32_bf16 v[60:63], v[132:135], v[216:219], v[60:63]
	v_mfma_f32_16x16x32_bf16 v[56:59], v[140:143], v[216:219], v[56:59]
	v_mfma_f32_16x16x32_bf16 v[48:51], v[132:135], v[220:223], v[48:51]
	v_mfma_f32_16x16x32_bf16 v[40:43], v[140:143], v[220:223], v[40:43]
	v_mfma_f32_16x16x32_bf16 v[32:35], v[132:135], v[236:239], v[32:35]
	v_mfma_f32_16x16x32_bf16 v[24:27], v[140:143], v[236:239], v[24:27]
	v_mfma_f32_16x16x32_bf16 v[16:19], v[132:135], v[240:243], v[16:19]
	v_mfma_f32_16x16x32_bf16 v[8:11], v[140:143], v[240:243], v[8:11]
	s_setprio 0
	s_setprio 1
	v_mfma_f32_16x16x32_bf16 v[52:55], v[192:195], v[208:211], v[52:55]
	v_mfma_f32_16x16x32_bf16 v[44:47], v[200:203], v[208:211], v[44:47]
	v_mfma_f32_16x16x32_bf16 v[36:39], v[192:195], v[212:215], v[36:39]
	v_mfma_f32_16x16x32_bf16 v[28:31], v[200:203], v[212:215], v[28:31]
	v_mfma_f32_16x16x32_bf16 v[20:23], v[192:195], v[228:231], v[20:23]
	v_mfma_f32_16x16x32_bf16 v[12:15], v[200:203], v[228:231], v[12:15]
	v_mfma_f32_16x16x32_bf16 v[4:7], v[192:195], v[232:235], v[4:7]
	v_mfma_f32_16x16x32_bf16 v[0:3], v[200:203], v[232:235], v[0:3]
	v_mfma_f32_16x16x32_bf16 v[52:55], v[196:199], v[216:219], v[52:55]
	v_mfma_f32_16x16x32_bf16 v[44:47], v[204:207], v[216:219], v[44:47]
	v_mfma_f32_16x16x32_bf16 v[36:39], v[196:199], v[220:223], v[36:39]
	v_mfma_f32_16x16x32_bf16 v[28:31], v[204:207], v[220:223], v[28:31]
	v_mfma_f32_16x16x32_bf16 v[20:23], v[196:199], v[236:239], v[20:23]
	v_mfma_f32_16x16x32_bf16 v[12:15], v[204:207], v[236:239], v[12:15]
	v_mfma_f32_16x16x32_bf16 v[4:7], v[196:199], v[240:243], v[4:7]
	v_mfma_f32_16x16x32_bf16 v[0:3], v[204:207], v[240:243], v[0:3]
	s_setprio 0
	s_barrier
	s_add_i32 s7, 0, 0x18000
	s_add_i32 s97, 0, 0x1c000
	v_add_u32_e32 v128, s7, v171
	v_add_u32_e32 v132, s7, v172
	v_add_u32_e32 v192, s97, v171
	v_add_u32_e32 v196, s97, v172
	ds_read_b128 v[128:131], v128
	ds_read_b128 v[132:135], v132
	ds_read_b128 v[136:139], v186
	ds_read_b128 v[140:143], v187
	ds_read_b128 v[192:195], v192
	ds_read_b128 v[196:199], v196
	ds_read_b128 v[200:203], v188
	ds_read_b128 v[204:207], v189
	s_add_u32 s26, s66, 0x80000
	s_addc_u32 s27, s67, 0
	s_mov_b32 m0, s78
	ds_read_b128 v[208:211], v184 offset:32768
	ds_read_b128 v[212:215], v184 offset:34816
	ds_read_b128 v[216:219], v185 offset:32768
	ds_read_b128 v[220:223], v185 offset:34816
	ds_read_b128 v[228:231], v184 offset:36864
	ds_read_b128 v[232:235], v184 offset:38912
	ds_read_b128 v[236:239], v185 offset:36864
	ds_read_b128 v[240:243], v185 offset:38912
	global_load_lds_dwordx4 v150, s[26:27]
	s_mov_b32 m0, s79
	s_nop 0
	global_load_lds_dwordx4 v146, s[26:27]
	s_waitcnt vmcnt(8)
	s_waitcnt lgkmcnt(0)
	s_barrier
	s_setprio 1
	s_waitcnt lgkmcnt(0)
	v_mfma_f32_16x16x32_bf16 v[124:127], v[128:131], v[208:211], v[124:127]
	v_mfma_f32_16x16x32_bf16 v[120:123], v[136:139], v[208:211], v[120:123]
	v_mfma_f32_16x16x32_bf16 v[112:115], v[128:131], v[212:215], v[112:115]
	v_mfma_f32_16x16x32_bf16 v[104:107], v[136:139], v[212:215], v[104:107]
	v_mfma_f32_16x16x32_bf16 v[96:99], v[128:131], v[228:231], v[96:99]
	v_mfma_f32_16x16x32_bf16 v[88:91], v[136:139], v[228:231], v[88:91]
	v_mfma_f32_16x16x32_bf16 v[80:83], v[128:131], v[232:235], v[80:83]
	v_mfma_f32_16x16x32_bf16 v[72:75], v[136:139], v[232:235], v[72:75]
	v_mfma_f32_16x16x32_bf16 v[124:127], v[132:135], v[216:219], v[124:127]
	v_mfma_f32_16x16x32_bf16 v[120:123], v[140:143], v[216:219], v[120:123]
	v_mfma_f32_16x16x32_bf16 v[112:115], v[132:135], v[220:223], v[112:115]
	v_mfma_f32_16x16x32_bf16 v[104:107], v[140:143], v[220:223], v[104:107]
	v_mfma_f32_16x16x32_bf16 v[96:99], v[132:135], v[236:239], v[96:99]
	v_mfma_f32_16x16x32_bf16 v[88:91], v[140:143], v[236:239], v[88:91]
	v_mfma_f32_16x16x32_bf16 v[80:83], v[132:135], v[240:243], v[80:83]
	v_mfma_f32_16x16x32_bf16 v[72:75], v[140:143], v[240:243], v[72:75]
	s_setprio 0
	s_setprio 1
	v_mfma_f32_16x16x32_bf16 v[116:119], v[192:195], v[208:211], v[116:119]
	v_mfma_f32_16x16x32_bf16 v[108:111], v[200:203], v[208:211], v[108:111]
	v_mfma_f32_16x16x32_bf16 v[100:103], v[192:195], v[212:215], v[100:103]
	v_mfma_f32_16x16x32_bf16 v[92:95], v[200:203], v[212:215], v[92:95]
	v_mfma_f32_16x16x32_bf16 v[84:87], v[192:195], v[228:231], v[84:87]
	v_mfma_f32_16x16x32_bf16 v[76:79], v[200:203], v[228:231], v[76:79]
	v_mfma_f32_16x16x32_bf16 v[68:71], v[192:195], v[232:235], v[68:71]
	v_mfma_f32_16x16x32_bf16 v[64:67], v[200:203], v[232:235], v[64:67]
	v_mfma_f32_16x16x32_bf16 v[116:119], v[196:199], v[216:219], v[116:119]
	v_mfma_f32_16x16x32_bf16 v[108:111], v[204:207], v[216:219], v[108:111]
	v_mfma_f32_16x16x32_bf16 v[100:103], v[196:199], v[220:223], v[100:103]
	v_mfma_f32_16x16x32_bf16 v[92:95], v[204:207], v[220:223], v[92:95]
	v_mfma_f32_16x16x32_bf16 v[84:87], v[196:199], v[236:239], v[84:87]
	v_mfma_f32_16x16x32_bf16 v[76:79], v[204:207], v[236:239], v[76:79]
	v_mfma_f32_16x16x32_bf16 v[68:71], v[196:199], v[240:243], v[68:71]
	v_mfma_f32_16x16x32_bf16 v[64:67], v[204:207], v[240:243], v[64:67]
	s_setprio 0
	s_barrier
	s_add_i32 s7, s7, s72
	s_add_i32 m0, s7, 0xffffff80
	ds_read_b128 v[208:211], v184 offset:49152
	ds_read_b128 v[212:215], v184 offset:51200
	ds_read_b128 v[216:219], v185 offset:49152
	ds_read_b128 v[220:223], v185 offset:51200
	ds_read_b128 v[228:231], v184 offset:53248
	ds_read_b128 v[232:235], v184 offset:55296
	ds_read_b128 v[236:239], v185 offset:53248
	ds_read_b128 v[240:243], v185 offset:55296
	global_load_lds_dwordx4 v148, s[64:65] offset:128
	s_add_i32 m0, s7, 0x1f80
	s_add_u32 s26, s64, 0x80080
	s_addc_u32 s27, s65, 0
	s_add_i32 s7, s97, s72
	global_load_lds_dwordx4 v144, s[64:65] offset:128
	s_mov_b32 m0, s7
	s_nop 0
	global_load_lds_dwordx4 v148, s[26:27]
	s_add_i32 m0, s7, 0x2000
	s_nop 0
	global_load_lds_dwordx4 v144, s[26:27]
	s_add_i32 m0, s80, 0xffffff80
	s_nop 0
	global_load_lds_dwordx4 v150, s[66:67] offset:128
	s_add_i32 m0, s81, 0xffffff80
	s_nop 0
	global_load_lds_dwordx4 v146, s[66:67] offset:128
	s_waitcnt vmcnt(8)
	s_waitcnt lgkmcnt(0)
	s_barrier
	s_setprio 1
	s_waitcnt lgkmcnt(0)
	v_mfma_f32_16x16x32_bf16 v[60:63], v[128:131], v[208:211], v[60:63]
	v_mfma_f32_16x16x32_bf16 v[56:59], v[136:139], v[208:211], v[56:59]
	v_mfma_f32_16x16x32_bf16 v[48:51], v[128:131], v[212:215], v[48:51]
	v_mfma_f32_16x16x32_bf16 v[40:43], v[136:139], v[212:215], v[40:43]
	v_mfma_f32_16x16x32_bf16 v[32:35], v[128:131], v[228:231], v[32:35]
	v_mfma_f32_16x16x32_bf16 v[24:27], v[136:139], v[228:231], v[24:27]
	v_mfma_f32_16x16x32_bf16 v[16:19], v[128:131], v[232:235], v[16:19]
	v_mfma_f32_16x16x32_bf16 v[8:11], v[136:139], v[232:235], v[8:11]
	v_mfma_f32_16x16x32_bf16 v[60:63], v[132:135], v[216:219], v[60:63]
	v_mfma_f32_16x16x32_bf16 v[56:59], v[140:143], v[216:219], v[56:59]
	v_mfma_f32_16x16x32_bf16 v[48:51], v[132:135], v[220:223], v[48:51]
	v_mfma_f32_16x16x32_bf16 v[40:43], v[140:143], v[220:223], v[40:43]
	v_mfma_f32_16x16x32_bf16 v[32:35], v[132:135], v[236:239], v[32:35]
	v_mfma_f32_16x16x32_bf16 v[24:27], v[140:143], v[236:239], v[24:27]
	v_mfma_f32_16x16x32_bf16 v[16:19], v[132:135], v[240:243], v[16:19]
	v_mfma_f32_16x16x32_bf16 v[8:11], v[140:143], v[240:243], v[8:11]
	s_setprio 0
	s_setprio 1
	v_mfma_f32_16x16x32_bf16 v[52:55], v[192:195], v[208:211], v[52:55]
	v_mfma_f32_16x16x32_bf16 v[44:47], v[200:203], v[208:211], v[44:47]
	v_mfma_f32_16x16x32_bf16 v[36:39], v[192:195], v[212:215], v[36:39]
	v_mfma_f32_16x16x32_bf16 v[28:31], v[200:203], v[212:215], v[28:31]
	v_mfma_f32_16x16x32_bf16 v[20:23], v[192:195], v[228:231], v[20:23]
	v_mfma_f32_16x16x32_bf16 v[12:15], v[200:203], v[228:231], v[12:15]
	v_mfma_f32_16x16x32_bf16 v[4:7], v[192:195], v[232:235], v[4:7]
	v_mfma_f32_16x16x32_bf16 v[0:3], v[200:203], v[232:235], v[0:3]
	v_mfma_f32_16x16x32_bf16 v[52:55], v[196:199], v[216:219], v[52:55]
	v_mfma_f32_16x16x32_bf16 v[44:47], v[204:207], v[216:219], v[44:47]
	v_mfma_f32_16x16x32_bf16 v[36:39], v[196:199], v[220:223], v[36:39]
	v_mfma_f32_16x16x32_bf16 v[28:31], v[204:207], v[220:223], v[28:31]
	v_mfma_f32_16x16x32_bf16 v[20:23], v[196:199], v[236:239], v[20:23]
	v_mfma_f32_16x16x32_bf16 v[12:15], v[204:207], v[236:239], v[12:15]
	v_mfma_f32_16x16x32_bf16 v[4:7], v[196:199], v[240:243], v[4:7]
	v_mfma_f32_16x16x32_bf16 v[0:3], v[204:207], v[240:243], v[0:3]
	s_setprio 0
	s_barrier
	s_add_i32 s96, s96, 2
	s_add_u32 s4, s4, 0x100
	s_addc_u32 s5, s5, 0
	s_add_u32 s94, s94, 0x100
	s_addc_u32 s95, s95, 0
	s_cmp_gt_u32 s96, 29
	s_cbranch_scc0 .LBB0_802
	s_and_b64 vcc, exec, s[46:47]
	s_cbranch_vccz .LBB0_805
	s_barrier

.LBB0_824:
	ds_read_b128 v[168:171], v149
	ds_read_b128 v[172:175], v150
	ds_read_b128 v[176:179], v151
	ds_read_b128 v[180:183], v152
	ds_read_b128 v[184:187], v153
	ds_read_b128 v[188:191], v154
	ds_read_b128 v[192:195], v155
	ds_read_b128 v[196:199], v156
	s_add_u32 s7, s4, 0xfff80080
	s_addc_u32 s26, s5, -1
	s_cmp_eq_u32 s80, 28
	s_cselect_b32 s53, s31, s26
	s_cselect_b32 s52, s74, s7
	s_cselect_b32 s51, s43, s79
	s_cselect_b32 s50, s75, s78
	s_add_i32 m0, s57, 0xc000
	ds_read_b128 v[200:203], v157
	ds_read_b128 v[204:207], v157 offset:2048
	ds_read_b128 v[208:211], v158
	ds_read_b128 v[212:215], v158 offset:2048
	ds_read_b128 v[216:219], v157 offset:4096
	ds_read_b128 v[220:223], v157 offset:6144
	ds_read_b128 v[228:231], v158 offset:4096
	ds_read_b128 v[232:235], v158 offset:6144
	global_load_lds_dwordx4 v136, s[4:5]
	s_add_i32 m0, s57, 0xe000
	s_nop 0
	global_load_lds_dwordx4 v138, s[4:5]
	s_waitcnt vmcnt(8)
	s_waitcnt lgkmcnt(0)
	s_barrier
	s_setprio 1
	s_waitcnt lgkmcnt(0)
	v_mfma_f32_16x16x32_bf16 v[124:127], v[168:171], v[200:203], v[124:127]
	v_mfma_f32_16x16x32_bf16 v[116:119], v[176:179], v[200:203], v[116:119]
	v_mfma_f32_16x16x32_bf16 v[108:111], v[168:171], v[204:207], v[108:111]
	v_mfma_f32_16x16x32_bf16 v[100:103], v[176:179], v[204:207], v[100:103]
	v_mfma_f32_16x16x32_bf16 v[92:95], v[168:171], v[216:219], v[92:95]
	v_mfma_f32_16x16x32_bf16 v[84:87], v[176:179], v[216:219], v[84:87]
	v_mfma_f32_16x16x32_bf16 v[76:79], v[168:171], v[220:223], v[76:79]
	v_mfma_f32_16x16x32_bf16 v[68:71], v[176:179], v[220:223], v[68:71]
	v_mfma_f32_16x16x32_bf16 v[124:127], v[172:175], v[208:211], v[124:127]
	v_mfma_f32_16x16x32_bf16 v[116:119], v[180:183], v[208:211], v[116:119]
	v_mfma_f32_16x16x32_bf16 v[108:111], v[172:175], v[212:215], v[108:111]
	v_mfma_f32_16x16x32_bf16 v[100:103], v[180:183], v[212:215], v[100:103]
	v_mfma_f32_16x16x32_bf16 v[92:95], v[172:175], v[228:231], v[92:95]
	v_mfma_f32_16x16x32_bf16 v[84:87], v[180:183], v[228:231], v[84:87]
	v_mfma_f32_16x16x32_bf16 v[76:79], v[172:175], v[232:235], v[76:79]
	v_mfma_f32_16x16x32_bf16 v[68:71], v[180:183], v[232:235], v[68:71]
	s_setprio 0
	s_setprio 1
	v_mfma_f32_16x16x32_bf16 v[120:123], v[184:187], v[200:203], v[120:123]
	v_mfma_f32_16x16x32_bf16 v[112:115], v[192:195], v[200:203], v[112:115]
	v_mfma_f32_16x16x32_bf16 v[104:107], v[184:187], v[204:207], v[104:107]
	v_mfma_f32_16x16x32_bf16 v[96:99], v[192:195], v[204:207], v[96:99]
	v_mfma_f32_16x16x32_bf16 v[88:91], v[184:187], v[216:219], v[88:91]
	v_mfma_f32_16x16x32_bf16 v[80:83], v[192:195], v[216:219], v[80:83]
	v_mfma_f32_16x16x32_bf16 v[72:75], v[184:187], v[220:223], v[72:75]
	v_mfma_f32_16x16x32_bf16 v[64:67], v[192:195], v[220:223], v[64:67]
	v_mfma_f32_16x16x32_bf16 v[120:123], v[188:191], v[208:211], v[120:123]
	v_mfma_f32_16x16x32_bf16 v[112:115], v[196:199], v[208:211], v[112:115]
	v_mfma_f32_16x16x32_bf16 v[104:107], v[188:191], v[212:215], v[104:107]
	v_mfma_f32_16x16x32_bf16 v[96:99], v[196:199], v[212:215], v[96:99]
	v_mfma_f32_16x16x32_bf16 v[88:91], v[188:191], v[228:231], v[88:91]
	v_mfma_f32_16x16x32_bf16 v[80:83], v[196:199], v[228:231], v[80:83]
	v_mfma_f32_16x16x32_bf16 v[72:75], v[188:191], v[232:235], v[72:75]
	v_mfma_f32_16x16x32_bf16 v[64:67], v[196:199], v[232:235], v[64:67]
	s_setprio 0
	s_barrier
	s_add_i32 s7, s65, s54
	s_mov_b32 m0, s7
	ds_read_b128 v[200:203], v157 offset:16384
	ds_read_b128 v[204:207], v157 offset:18432
	ds_read_b128 v[208:211], v158 offset:16384
	ds_read_b128 v[212:215], v158 offset:18432
	ds_read_b128 v[216:219], v157 offset:20480
	ds_read_b128 v[220:223], v157 offset:22528
	ds_read_b128 v[228:231], v158 offset:20480
	ds_read_b128 v[232:235], v158 offset:22528
	global_load_lds_dwordx4 v132, s[50:51]
	s_add_i32 m0, s7, 0x2000
	s_add_u32 s26, s50, 0x80000
	s_addc_u32 s27, s51, 0
	s_add_i32 s7, s66, s54
	global_load_lds_dwordx4 v128, s[50:51]
	s_mov_b32 m0, s7
	s_nop 0
	global_load_lds_dwordx4 v132, s[26:27]
	s_add_i32 m0, s7, 0x2000
	s_nop 0
	global_load_lds_dwordx4 v128, s[26:27]
	s_mov_b32 m0, s57
	s_nop 0
	global_load_lds_dwordx4 v134, s[52:53]
	s_mov_b32 m0, s58
	s_nop 0
	global_load_lds_dwordx4 v130, s[52:53]
	s_waitcnt vmcnt(8)
	s_waitcnt lgkmcnt(0)
	s_barrier
	s_setprio 1
	s_waitcnt lgkmcnt(0)
	v_mfma_f32_16x16x32_bf16 v[60:63], v[168:171], v[200:203], v[60:63]
	v_mfma_f32_16x16x32_bf16 v[52:55], v[176:179], v[200:203], v[52:55]
	v_mfma_f32_16x16x32_bf16 v[44:47], v[168:171], v[204:207], v[44:47]
	v_mfma_f32_16x16x32_bf16 v[36:39], v[176:179], v[204:207], v[36:39]
	v_mfma_f32_16x16x32_bf16 v[28:31], v[168:171], v[216:219], v[28:31]
	v_mfma_f32_16x16x32_bf16 v[20:23], v[176:179], v[216:219], v[20:23]
	v_mfma_f32_16x16x32_bf16 v[12:15], v[168:171], v[220:223], v[12:15]
	v_mfma_f32_16x16x32_bf16 v[4:7], v[176:179], v[220:223], v[4:7]
	v_mfma_f32_16x16x32_bf16 v[60:63], v[172:175], v[208:211], v[60:63]
	v_mfma_f32_16x16x32_bf16 v[52:55], v[180:183], v[208:211], v[52:55]
	v_mfma_f32_16x16x32_bf16 v[44:47], v[172:175], v[212:215], v[44:47]
	v_mfma_f32_16x16x32_bf16 v[36:39], v[180:183], v[212:215], v[36:39]
	v_mfma_f32_16x16x32_bf16 v[28:31], v[172:175], v[228:231], v[28:31]
	v_mfma_f32_16x16x32_bf16 v[20:23], v[180:183], v[228:231], v[20:23]
	v_mfma_f32_16x16x32_bf16 v[12:15], v[172:175], v[232:235], v[12:15]
	v_mfma_f32_16x16x32_bf16 v[4:7], v[180:183], v[232:235], v[4:7]
	s_setprio 0
	s_setprio 1
	v_mfma_f32_16x16x32_bf16 v[56:59], v[184:187], v[200:203], v[56:59]
	v_mfma_f32_16x16x32_bf16 v[48:51], v[192:195], v[200:203], v[48:51]
	v_mfma_f32_16x16x32_bf16 v[40:43], v[184:187], v[204:207], v[40:43]
	v_mfma_f32_16x16x32_bf16 v[32:35], v[192:195], v[204:207], v[32:35]
	v_mfma_f32_16x16x32_bf16 v[24:27], v[184:187], v[216:219], v[24:27]
	v_mfma_f32_16x16x32_bf16 v[16:19], v[192:195], v[216:219], v[16:19]
	v_mfma_f32_16x16x32_bf16 v[8:11], v[184:187], v[220:223], v[8:11]
	v_mfma_f32_16x16x32_bf16 v[0:3], v[192:195], v[220:223], v[0:3]
	v_mfma_f32_16x16x32_bf16 v[56:59], v[188:191], v[208:211], v[56:59]
	v_mfma_f32_16x16x32_bf16 v[48:51], v[196:199], v[208:211], v[48:51]
	v_mfma_f32_16x16x32_bf16 v[40:43], v[188:191], v[212:215], v[40:43]
	v_mfma_f32_16x16x32_bf16 v[32:35], v[196:199], v[212:215], v[32:35]
	v_mfma_f32_16x16x32_bf16 v[24:27], v[188:191], v[228:231], v[24:27]
	v_mfma_f32_16x16x32_bf16 v[16:19], v[196:199], v[228:231], v[16:19]
	v_mfma_f32_16x16x32_bf16 v[8:11], v[188:191], v[232:235], v[8:11]
	v_mfma_f32_16x16x32_bf16 v[0:3], v[196:199], v[232:235], v[0:3]
	s_setprio 0
	s_barrier
	s_add_i32 s7, 0, 0x18000
	v_add_u32_e32 v167, s7, v144
	v_add_u32_e32 v172, s7, v145
	s_add_i32 s81, 0, 0x1c000
	ds_read_b128 v[168:171], v167
	ds_read_b128 v[172:175], v172
	ds_read_b128 v[176:179], v159
	ds_read_b128 v[180:183], v160
	v_add_u32_e32 v167, s81, v144
	v_add_u32_e32 v188, s81, v145
	ds_read_b128 v[184:187], v167
	ds_read_b128 v[188:191], v188
	ds_read_b128 v[192:195], v161
	ds_read_b128 v[196:199], v164
	s_add_u32 s26, s52, 0x80000
	s_addc_u32 s27, s53, 0
	s_mov_b32 m0, s59
	ds_read_b128 v[200:203], v157 offset:32768
	ds_read_b128 v[204:207], v157 offset:34816
	ds_read_b128 v[208:211], v158 offset:32768
	ds_read_b128 v[212:215], v158 offset:34816
	ds_read_b128 v[216:219], v157 offset:36864
	ds_read_b128 v[220:223], v157 offset:38912
	ds_read_b128 v[228:231], v158 offset:36864
	ds_read_b128 v[232:235], v158 offset:38912
	global_load_lds_dwordx4 v134, s[26:27]
	s_mov_b32 m0, s60
	s_nop 0
	global_load_lds_dwordx4 v130, s[26:27]
	s_waitcnt vmcnt(8)
	s_waitcnt lgkmcnt(0)
	s_barrier
	s_setprio 1
	s_waitcnt lgkmcnt(0)
	v_mfma_f32_16x16x32_bf16 v[124:127], v[168:171], v[200:203], v[124:127]
	v_mfma_f32_16x16x32_bf16 v[116:119], v[176:179], v[200:203], v[116:119]
	v_mfma_f32_16x16x32_bf16 v[108:111], v[168:171], v[204:207], v[108:111]
	v_mfma_f32_16x16x32_bf16 v[100:103], v[176:179], v[204:207], v[100:103]
	v_mfma_f32_16x16x32_bf16 v[92:95], v[168:171], v[216:219], v[92:95]
	v_mfma_f32_16x16x32_bf16 v[84:87], v[176:179], v[216:219], v[84:87]
	v_mfma_f32_16x16x32_bf16 v[76:79], v[168:171], v[220:223], v[76:79]
	v_mfma_f32_16x16x32_bf16 v[68:71], v[176:179], v[220:223], v[68:71]
	v_mfma_f32_16x16x32_bf16 v[124:127], v[172:175], v[208:211], v[124:127]
	v_mfma_f32_16x16x32_bf16 v[116:119], v[180:183], v[208:211], v[116:119]
	v_mfma_f32_16x16x32_bf16 v[108:111], v[172:175], v[212:215], v[108:111]
	v_mfma_f32_16x16x32_bf16 v[100:103], v[180:183], v[212:215], v[100:103]
	v_mfma_f32_16x16x32_bf16 v[92:95], v[172:175], v[228:231], v[92:95]
	v_mfma_f32_16x16x32_bf16 v[84:87], v[180:183], v[228:231], v[84:87]
	v_mfma_f32_16x16x32_bf16 v[76:79], v[172:175], v[232:235], v[76:79]
	v_mfma_f32_16x16x32_bf16 v[68:71], v[180:183], v[232:235], v[68:71]
	s_setprio 0
	s_setprio 1
	v_mfma_f32_16x16x32_bf16 v[120:123], v[184:187], v[200:203], v[120:123]
	v_mfma_f32_16x16x32_bf16 v[112:115], v[192:195], v[200:203], v[112:115]
	v_mfma_f32_16x16x32_bf16 v[104:107], v[184:187], v[204:207], v[104:107]
	v_mfma_f32_16x16x32_bf16 v[96:99], v[192:195], v[204:207], v[96:99]
	v_mfma_f32_16x16x32_bf16 v[88:91], v[184:187], v[216:219], v[88:91]
	v_mfma_f32_16x16x32_bf16 v[80:83], v[192:195], v[216:219], v[80:83]
	v_mfma_f32_16x16x32_bf16 v[72:75], v[184:187], v[220:223], v[72:75]
	v_mfma_f32_16x16x32_bf16 v[64:67], v[192:195], v[220:223], v[64:67]
	v_mfma_f32_16x16x32_bf16 v[120:123], v[188:191], v[208:211], v[120:123]
	v_mfma_f32_16x16x32_bf16 v[112:115], v[196:199], v[208:211], v[112:115]
	v_mfma_f32_16x16x32_bf16 v[104:107], v[188:191], v[212:215], v[104:107]
	v_mfma_f32_16x16x32_bf16 v[96:99], v[196:199], v[212:215], v[96:99]
	v_mfma_f32_16x16x32_bf16 v[88:91], v[188:191], v[228:231], v[88:91]
	v_mfma_f32_16x16x32_bf16 v[80:83], v[196:199], v[228:231], v[80:83]
	v_mfma_f32_16x16x32_bf16 v[72:75], v[188:191], v[232:235], v[72:75]
	v_mfma_f32_16x16x32_bf16 v[64:67], v[196:199], v[232:235], v[64:67]
	s_setprio 0
	s_barrier
	s_add_i32 s7, s7, s54
	s_add_i32 m0, s7, 0xffffff80
	ds_read_b128 v[200:203], v157 offset:49152
	ds_read_b128 v[204:207], v157 offset:51200
	ds_read_b128 v[208:211], v158 offset:49152
	ds_read_b128 v[212:215], v158 offset:51200
	ds_read_b128 v[216:219], v157 offset:53248
	ds_read_b128 v[220:223], v157 offset:55296
	ds_read_b128 v[228:231], v158 offset:53248
	ds_read_b128 v[232:235], v158 offset:55296
	global_load_lds_dwordx4 v132, s[50:51] offset:128
	s_add_i32 m0, s7, 0x1f80
	s_add_u32 s26, s50, 0x80080
	s_addc_u32 s27, s51, 0
	s_add_i32 s7, s81, s54
	global_load_lds_dwordx4 v128, s[50:51] offset:128
	s_mov_b32 m0, s7
	s_nop 0
	global_load_lds_dwordx4 v132, s[26:27]
	s_add_i32 m0, s7, 0x2000
	s_nop 0
	global_load_lds_dwordx4 v128, s[26:27]
	s_add_i32 m0, s61, 0xffffff80
	s_nop 0
	global_load_lds_dwordx4 v134, s[52:53] offset:128
	s_add_i32 m0, s62, 0xffffff80
	s_nop 0
	global_load_lds_dwordx4 v130, s[52:53] offset:128
	s_waitcnt vmcnt(8)
	s_waitcnt lgkmcnt(0)
	s_barrier
	s_setprio 1
	s_waitcnt lgkmcnt(0)
	v_mfma_f32_16x16x32_bf16 v[60:63], v[168:171], v[200:203], v[60:63]
	v_mfma_f32_16x16x32_bf16 v[52:55], v[176:179], v[200:203], v[52:55]
	v_mfma_f32_16x16x32_bf16 v[44:47], v[168:171], v[204:207], v[44:47]
	v_mfma_f32_16x16x32_bf16 v[36:39], v[176:179], v[204:207], v[36:39]
	v_mfma_f32_16x16x32_bf16 v[28:31], v[168:171], v[216:219], v[28:31]
	v_mfma_f32_16x16x32_bf16 v[20:23], v[176:179], v[216:219], v[20:23]
	v_mfma_f32_16x16x32_bf16 v[12:15], v[168:171], v[220:223], v[12:15]
	v_mfma_f32_16x16x32_bf16 v[4:7], v[176:179], v[220:223], v[4:7]
	v_mfma_f32_16x16x32_bf16 v[60:63], v[172:175], v[208:211], v[60:63]
	v_mfma_f32_16x16x32_bf16 v[52:55], v[180:183], v[208:211], v[52:55]
	v_mfma_f32_16x16x32_bf16 v[44:47], v[172:175], v[212:215], v[44:47]
	v_mfma_f32_16x16x32_bf16 v[36:39], v[180:183], v[212:215], v[36:39]
	v_mfma_f32_16x16x32_bf16 v[28:31], v[172:175], v[228:231], v[28:31]
	v_mfma_f32_16x16x32_bf16 v[20:23], v[180:183], v[228:231], v[20:23]
	v_mfma_f32_16x16x32_bf16 v[12:15], v[172:175], v[232:235], v[12:15]
	v_mfma_f32_16x16x32_bf16 v[4:7], v[180:183], v[232:235], v[4:7]
	s_setprio 0
	s_setprio 1
	v_mfma_f32_16x16x32_bf16 v[56:59], v[184:187], v[200:203], v[56:59]
	v_mfma_f32_16x16x32_bf16 v[48:51], v[192:195], v[200:203], v[48:51]
	v_mfma_f32_16x16x32_bf16 v[40:43], v[184:187], v[204:207], v[40:43]
	v_mfma_f32_16x16x32_bf16 v[32:35], v[192:195], v[204:207], v[32:35]
	v_mfma_f32_16x16x32_bf16 v[24:27], v[184:187], v[216:219], v[24:27]
	v_mfma_f32_16x16x32_bf16 v[16:19], v[192:195], v[216:219], v[16:19]
	v_mfma_f32_16x16x32_bf16 v[8:11], v[184:187], v[220:223], v[8:11]
	v_mfma_f32_16x16x32_bf16 v[0:3], v[192:195], v[220:223], v[0:3]
	v_mfma_f32_16x16x32_bf16 v[56:59], v[188:191], v[208:211], v[56:59]
	v_mfma_f32_16x16x32_bf16 v[48:51], v[196:199], v[208:211], v[48:51]
	v_mfma_f32_16x16x32_bf16 v[40:43], v[188:191], v[212:215], v[40:43]
	v_mfma_f32_16x16x32_bf16 v[32:35], v[196:199], v[212:215], v[32:35]
	v_mfma_f32_16x16x32_bf16 v[24:27], v[188:191], v[228:231], v[24:27]
	v_mfma_f32_16x16x32_bf16 v[16:19], v[196:199], v[228:231], v[16:19]
	v_mfma_f32_16x16x32_bf16 v[8:11], v[188:191], v[232:235], v[8:11]
	v_mfma_f32_16x16x32_bf16 v[0:3], v[196:199], v[232:235], v[0:3]
	s_setprio 0
	s_barrier
	s_add_i32 s80, s80, 2
	s_add_u32 s4, s4, 0x100
	s_addc_u32 s5, s5, 0
	s_add_u32 s78, s78, 0x100
	s_addc_u32 s79, s79, 0
	s_cmp_gt_u32 s80, 29
	s_cbranch_scc0 .LBB0_824
	s_and_b64 vcc, exec, s[40:41]
	s_cbranch_vccz .LBB0_827
	s_barrier

.LBB0_1047:
	ds_read_b128 v[168:171], v152
	ds_read_b128 v[172:175], v153
	ds_read_b128 v[176:179], v154
	ds_read_b128 v[180:183], v155
	ds_read_b128 v[184:187], v156
	ds_read_b128 v[188:191], v157
	ds_read_b128 v[192:195], v158
	ds_read_b128 v[196:199], v159
	s_add_u32 s7, s4, 0xfff80080
	s_addc_u32 s26, s5, -1
	s_cmp_eq_u32 s87, 28
	s_cselect_b32 s59, s15, s26
	s_cselect_b32 s58, s83, s7
	s_cselect_b32 s57, s51, s86
	s_cselect_b32 s56, s84, s85
	s_add_i32 m0, s63, 0xc000
	ds_read_b128 v[200:203], v160
	ds_read_b128 v[204:207], v160 offset:2048
	ds_read_b128 v[208:211], v161
	ds_read_b128 v[212:215], v161 offset:2048
	ds_read_b128 v[216:219], v160 offset:4096
	ds_read_b128 v[220:223], v160 offset:6144
	ds_read_b128 v[228:231], v161 offset:4096
	ds_read_b128 v[232:235], v161 offset:6144
	global_load_lds_dwordx4 v136, s[4:5]
	s_add_i32 m0, s63, 0xe000
	s_nop 0
	global_load_lds_dwordx4 v138, s[4:5]
	s_waitcnt vmcnt(8)
	s_waitcnt lgkmcnt(0)
	s_barrier
	s_setprio 1
	s_waitcnt lgkmcnt(0)
	v_mfma_f32_16x16x32_bf16 v[124:127], v[168:171], v[200:203], v[124:127]
	v_mfma_f32_16x16x32_bf16 v[120:123], v[176:179], v[200:203], v[120:123]
	v_mfma_f32_16x16x32_bf16 v[108:111], v[168:171], v[204:207], v[108:111]
	v_mfma_f32_16x16x32_bf16 v[104:107], v[176:179], v[204:207], v[104:107]
	v_mfma_f32_16x16x32_bf16 v[92:95], v[168:171], v[216:219], v[92:95]
	v_mfma_f32_16x16x32_bf16 v[88:91], v[176:179], v[216:219], v[88:91]
	v_mfma_f32_16x16x32_bf16 v[76:79], v[168:171], v[220:223], v[76:79]
	v_mfma_f32_16x16x32_bf16 v[72:75], v[176:179], v[220:223], v[72:75]
	v_mfma_f32_16x16x32_bf16 v[124:127], v[172:175], v[208:211], v[124:127]
	v_mfma_f32_16x16x32_bf16 v[120:123], v[180:183], v[208:211], v[120:123]
	v_mfma_f32_16x16x32_bf16 v[108:111], v[172:175], v[212:215], v[108:111]
	v_mfma_f32_16x16x32_bf16 v[104:107], v[180:183], v[212:215], v[104:107]
	v_mfma_f32_16x16x32_bf16 v[92:95], v[172:175], v[228:231], v[92:95]
	v_mfma_f32_16x16x32_bf16 v[88:91], v[180:183], v[228:231], v[88:91]
	v_mfma_f32_16x16x32_bf16 v[76:79], v[172:175], v[232:235], v[76:79]
	v_mfma_f32_16x16x32_bf16 v[72:75], v[180:183], v[232:235], v[72:75]
	s_setprio 0
	s_setprio 1
	v_mfma_f32_16x16x32_bf16 v[116:119], v[184:187], v[200:203], v[116:119]
	v_mfma_f32_16x16x32_bf16 v[112:115], v[192:195], v[200:203], v[112:115]
	v_mfma_f32_16x16x32_bf16 v[100:103], v[184:187], v[204:207], v[100:103]
	v_mfma_f32_16x16x32_bf16 v[96:99], v[192:195], v[204:207], v[96:99]
	v_mfma_f32_16x16x32_bf16 v[84:87], v[184:187], v[216:219], v[84:87]
	v_mfma_f32_16x16x32_bf16 v[80:83], v[192:195], v[216:219], v[80:83]
	v_mfma_f32_16x16x32_bf16 v[68:71], v[184:187], v[220:223], v[68:71]
	v_mfma_f32_16x16x32_bf16 v[64:67], v[192:195], v[220:223], v[64:67]
	v_mfma_f32_16x16x32_bf16 v[116:119], v[188:191], v[208:211], v[116:119]
	v_mfma_f32_16x16x32_bf16 v[112:115], v[196:199], v[208:211], v[112:115]
	v_mfma_f32_16x16x32_bf16 v[100:103], v[188:191], v[212:215], v[100:103]
	v_mfma_f32_16x16x32_bf16 v[96:99], v[196:199], v[212:215], v[96:99]
	v_mfma_f32_16x16x32_bf16 v[84:87], v[188:191], v[228:231], v[84:87]
	v_mfma_f32_16x16x32_bf16 v[80:83], v[196:199], v[228:231], v[80:83]
	v_mfma_f32_16x16x32_bf16 v[68:71], v[188:191], v[232:235], v[68:71]
	v_mfma_f32_16x16x32_bf16 v[64:67], v[196:199], v[232:235], v[64:67]
	s_setprio 0
	s_barrier
	s_add_i32 s7, s71, s61
	s_mov_b32 m0, s7
	ds_read_b128 v[200:203], v160 offset:16384
	ds_read_b128 v[204:207], v160 offset:18432
	ds_read_b128 v[208:211], v161 offset:16384
	ds_read_b128 v[212:215], v161 offset:18432
	ds_read_b128 v[216:219], v160 offset:20480
	ds_read_b128 v[220:223], v160 offset:22528
	ds_read_b128 v[228:231], v161 offset:20480
	ds_read_b128 v[232:235], v161 offset:22528
	global_load_lds_dwordx4 v132, s[56:57]
	s_add_i32 m0, s7, 0x2000
	s_add_u32 s26, s56, 0x80000
	s_addc_u32 s27, s57, 0
	s_add_i32 s7, s72, s61
	global_load_lds_dwordx4 v128, s[56:57]
	s_mov_b32 m0, s7
	s_nop 0
	global_load_lds_dwordx4 v132, s[26:27]
	s_add_i32 m0, s7, 0x2000
	s_nop 0
	global_load_lds_dwordx4 v128, s[26:27]
	s_mov_b32 m0, s63
	s_nop 0
	global_load_lds_dwordx4 v134, s[58:59]
	s_mov_b32 m0, s64
	s_nop 0
	global_load_lds_dwordx4 v130, s[58:59]
	s_waitcnt vmcnt(8)
	s_waitcnt lgkmcnt(0)
	s_barrier
	s_setprio 1
	s_waitcnt lgkmcnt(0)
	v_mfma_f32_16x16x32_bf16 v[60:63], v[168:171], v[200:203], v[60:63]
	v_mfma_f32_16x16x32_bf16 v[56:59], v[176:179], v[200:203], v[56:59]
	v_mfma_f32_16x16x32_bf16 v[48:51], v[168:171], v[204:207], v[48:51]
	v_mfma_f32_16x16x32_bf16 v[40:43], v[176:179], v[204:207], v[40:43]
	v_mfma_f32_16x16x32_bf16 v[32:35], v[168:171], v[216:219], v[32:35]
	v_mfma_f32_16x16x32_bf16 v[24:27], v[176:179], v[216:219], v[24:27]
	v_mfma_f32_16x16x32_bf16 v[16:19], v[168:171], v[220:223], v[16:19]
	v_mfma_f32_16x16x32_bf16 v[8:11], v[176:179], v[220:223], v[8:11]
	v_mfma_f32_16x16x32_bf16 v[60:63], v[172:175], v[208:211], v[60:63]
	v_mfma_f32_16x16x32_bf16 v[56:59], v[180:183], v[208:211], v[56:59]
	v_mfma_f32_16x16x32_bf16 v[48:51], v[172:175], v[212:215], v[48:51]
	v_mfma_f32_16x16x32_bf16 v[40:43], v[180:183], v[212:215], v[40:43]
	v_mfma_f32_16x16x32_bf16 v[32:35], v[172:175], v[228:231], v[32:35]
	v_mfma_f32_16x16x32_bf16 v[24:27], v[180:183], v[228:231], v[24:27]
	v_mfma_f32_16x16x32_bf16 v[16:19], v[172:175], v[232:235], v[16:19]
	v_mfma_f32_16x16x32_bf16 v[8:11], v[180:183], v[232:235], v[8:11]
	s_setprio 0
	s_setprio 1
	v_mfma_f32_16x16x32_bf16 v[52:55], v[184:187], v[200:203], v[52:55]
	v_mfma_f32_16x16x32_bf16 v[44:47], v[192:195], v[200:203], v[44:47]
	v_mfma_f32_16x16x32_bf16 v[36:39], v[184:187], v[204:207], v[36:39]
	v_mfma_f32_16x16x32_bf16 v[28:31], v[192:195], v[204:207], v[28:31]
	v_mfma_f32_16x16x32_bf16 v[20:23], v[184:187], v[216:219], v[20:23]
	v_mfma_f32_16x16x32_bf16 v[12:15], v[192:195], v[216:219], v[12:15]
	v_mfma_f32_16x16x32_bf16 v[4:7], v[184:187], v[220:223], v[4:7]
	v_mfma_f32_16x16x32_bf16 v[0:3], v[192:195], v[220:223], v[0:3]
	v_mfma_f32_16x16x32_bf16 v[52:55], v[188:191], v[208:211], v[52:55]
	v_mfma_f32_16x16x32_bf16 v[44:47], v[196:199], v[208:211], v[44:47]
	v_mfma_f32_16x16x32_bf16 v[36:39], v[188:191], v[212:215], v[36:39]
	v_mfma_f32_16x16x32_bf16 v[28:31], v[196:199], v[212:215], v[28:31]
	v_mfma_f32_16x16x32_bf16 v[20:23], v[188:191], v[228:231], v[20:23]
	v_mfma_f32_16x16x32_bf16 v[12:15], v[196:199], v[228:231], v[12:15]
	v_mfma_f32_16x16x32_bf16 v[4:7], v[188:191], v[232:235], v[4:7]
	v_mfma_f32_16x16x32_bf16 v[0:3], v[196:199], v[232:235], v[0:3]
	s_setprio 0
	s_barrier
	s_add_i32 s7, 0, 0x18000
	s_add_i32 s88, 0, 0x1c000
	v_add_u32_e32 v168, s7, v147
	v_add_u32_e32 v172, s7, v148
	v_add_u32_e32 v184, s88, v147
	v_add_u32_e32 v188, s88, v148
	ds_read_b128 v[168:171], v168
	ds_read_b128 v[172:175], v172
	ds_read_b128 v[176:179], v162
	ds_read_b128 v[180:183], v163
	ds_read_b128 v[184:187], v184
	ds_read_b128 v[188:191], v188
	ds_read_b128 v[192:195], v164
	ds_read_b128 v[196:199], v165
	s_add_u32 s26, s58, 0x80000
	s_addc_u32 s27, s59, 0
	s_mov_b32 m0, s65
	ds_read_b128 v[200:203], v160 offset:32768
	ds_read_b128 v[204:207], v160 offset:34816
	ds_read_b128 v[208:211], v161 offset:32768
	ds_read_b128 v[212:215], v161 offset:34816
	ds_read_b128 v[216:219], v160 offset:36864
	ds_read_b128 v[220:223], v160 offset:38912
	ds_read_b128 v[228:231], v161 offset:36864
	ds_read_b128 v[232:235], v161 offset:38912
	global_load_lds_dwordx4 v134, s[26:27]
	s_mov_b32 m0, s66
	s_nop 0
	global_load_lds_dwordx4 v130, s[26:27]
	s_waitcnt vmcnt(8)
	s_waitcnt lgkmcnt(0)
	s_barrier
	s_setprio 1
	s_waitcnt lgkmcnt(0)
	v_mfma_f32_16x16x32_bf16 v[124:127], v[168:171], v[200:203], v[124:127]
	v_mfma_f32_16x16x32_bf16 v[120:123], v[176:179], v[200:203], v[120:123]
	v_mfma_f32_16x16x32_bf16 v[108:111], v[168:171], v[204:207], v[108:111]
	v_mfma_f32_16x16x32_bf16 v[104:107], v[176:179], v[204:207], v[104:107]
	v_mfma_f32_16x16x32_bf16 v[92:95], v[168:171], v[216:219], v[92:95]
	v_mfma_f32_16x16x32_bf16 v[88:91], v[176:179], v[216:219], v[88:91]
	v_mfma_f32_16x16x32_bf16 v[76:79], v[168:171], v[220:223], v[76:79]
	v_mfma_f32_16x16x32_bf16 v[72:75], v[176:179], v[220:223], v[72:75]
	v_mfma_f32_16x16x32_bf16 v[124:127], v[172:175], v[208:211], v[124:127]
	v_mfma_f32_16x16x32_bf16 v[120:123], v[180:183], v[208:211], v[120:123]
	v_mfma_f32_16x16x32_bf16 v[108:111], v[172:175], v[212:215], v[108:111]
	v_mfma_f32_16x16x32_bf16 v[104:107], v[180:183], v[212:215], v[104:107]
	v_mfma_f32_16x16x32_bf16 v[92:95], v[172:175], v[228:231], v[92:95]
	v_mfma_f32_16x16x32_bf16 v[88:91], v[180:183], v[228:231], v[88:91]
	v_mfma_f32_16x16x32_bf16 v[76:79], v[172:175], v[232:235], v[76:79]
	v_mfma_f32_16x16x32_bf16 v[72:75], v[180:183], v[232:235], v[72:75]
	s_setprio 0
	s_setprio 1
	v_mfma_f32_16x16x32_bf16 v[116:119], v[184:187], v[200:203], v[116:119]
	v_mfma_f32_16x16x32_bf16 v[112:115], v[192:195], v[200:203], v[112:115]
	v_mfma_f32_16x16x32_bf16 v[100:103], v[184:187], v[204:207], v[100:103]
	v_mfma_f32_16x16x32_bf16 v[96:99], v[192:195], v[204:207], v[96:99]
	v_mfma_f32_16x16x32_bf16 v[84:87], v[184:187], v[216:219], v[84:87]
	v_mfma_f32_16x16x32_bf16 v[80:83], v[192:195], v[216:219], v[80:83]
	v_mfma_f32_16x16x32_bf16 v[68:71], v[184:187], v[220:223], v[68:71]
	v_mfma_f32_16x16x32_bf16 v[64:67], v[192:195], v[220:223], v[64:67]
	v_mfma_f32_16x16x32_bf16 v[116:119], v[188:191], v[208:211], v[116:119]
	v_mfma_f32_16x16x32_bf16 v[112:115], v[196:199], v[208:211], v[112:115]
	v_mfma_f32_16x16x32_bf16 v[100:103], v[188:191], v[212:215], v[100:103]
	v_mfma_f32_16x16x32_bf16 v[96:99], v[196:199], v[212:215], v[96:99]
	v_mfma_f32_16x16x32_bf16 v[84:87], v[188:191], v[228:231], v[84:87]
	v_mfma_f32_16x16x32_bf16 v[80:83], v[196:199], v[228:231], v[80:83]
	v_mfma_f32_16x16x32_bf16 v[68:71], v[188:191], v[232:235], v[68:71]
	v_mfma_f32_16x16x32_bf16 v[64:67], v[196:199], v[232:235], v[64:67]
	s_setprio 0
	s_barrier
	s_add_i32 s7, s7, s61
	s_add_i32 m0, s7, 0xffffff80
	ds_read_b128 v[200:203], v160 offset:49152
	ds_read_b128 v[204:207], v160 offset:51200
	ds_read_b128 v[208:211], v161 offset:49152
	ds_read_b128 v[212:215], v161 offset:51200
	ds_read_b128 v[216:219], v160 offset:53248
	ds_read_b128 v[220:223], v160 offset:55296
	ds_read_b128 v[228:231], v161 offset:53248
	ds_read_b128 v[232:235], v161 offset:55296
	global_load_lds_dwordx4 v132, s[56:57] offset:128
	s_add_i32 m0, s7, 0x1f80
	s_add_u32 s26, s56, 0x80080
	s_addc_u32 s27, s57, 0
	s_add_i32 s7, s88, s61
	global_load_lds_dwordx4 v128, s[56:57] offset:128
	s_mov_b32 m0, s7
	s_nop 0
	global_load_lds_dwordx4 v132, s[26:27]
	s_add_i32 m0, s7, 0x2000
	s_nop 0
	global_load_lds_dwordx4 v128, s[26:27]
	s_add_i32 m0, s68, 0xffffff80
	s_nop 0
	global_load_lds_dwordx4 v134, s[58:59] offset:128
	s_add_i32 m0, s69, 0xffffff80
	s_nop 0
	global_load_lds_dwordx4 v130, s[58:59] offset:128
	s_waitcnt vmcnt(8)
	s_waitcnt lgkmcnt(0)
	s_barrier
	s_setprio 1
	s_waitcnt lgkmcnt(0)
	v_mfma_f32_16x16x32_bf16 v[60:63], v[168:171], v[200:203], v[60:63]
	v_mfma_f32_16x16x32_bf16 v[56:59], v[176:179], v[200:203], v[56:59]
	v_mfma_f32_16x16x32_bf16 v[48:51], v[168:171], v[204:207], v[48:51]
	v_mfma_f32_16x16x32_bf16 v[40:43], v[176:179], v[204:207], v[40:43]
	v_mfma_f32_16x16x32_bf16 v[32:35], v[168:171], v[216:219], v[32:35]
	v_mfma_f32_16x16x32_bf16 v[24:27], v[176:179], v[216:219], v[24:27]
	v_mfma_f32_16x16x32_bf16 v[16:19], v[168:171], v[220:223], v[16:19]
	v_mfma_f32_16x16x32_bf16 v[8:11], v[176:179], v[220:223], v[8:11]
	v_mfma_f32_16x16x32_bf16 v[60:63], v[172:175], v[208:211], v[60:63]
	v_mfma_f32_16x16x32_bf16 v[56:59], v[180:183], v[208:211], v[56:59]
	v_mfma_f32_16x16x32_bf16 v[48:51], v[172:175], v[212:215], v[48:51]
	v_mfma_f32_16x16x32_bf16 v[40:43], v[180:183], v[212:215], v[40:43]
	v_mfma_f32_16x16x32_bf16 v[32:35], v[172:175], v[228:231], v[32:35]
	v_mfma_f32_16x16x32_bf16 v[24:27], v[180:183], v[228:231], v[24:27]
	v_mfma_f32_16x16x32_bf16 v[16:19], v[172:175], v[232:235], v[16:19]
	v_mfma_f32_16x16x32_bf16 v[8:11], v[180:183], v[232:235], v[8:11]
	s_setprio 0
	s_setprio 1
	v_mfma_f32_16x16x32_bf16 v[52:55], v[184:187], v[200:203], v[52:55]
	v_mfma_f32_16x16x32_bf16 v[44:47], v[192:195], v[200:203], v[44:47]
	v_mfma_f32_16x16x32_bf16 v[36:39], v[184:187], v[204:207], v[36:39]
	v_mfma_f32_16x16x32_bf16 v[28:31], v[192:195], v[204:207], v[28:31]
	v_mfma_f32_16x16x32_bf16 v[20:23], v[184:187], v[216:219], v[20:23]
	v_mfma_f32_16x16x32_bf16 v[12:15], v[192:195], v[216:219], v[12:15]
	v_mfma_f32_16x16x32_bf16 v[4:7], v[184:187], v[220:223], v[4:7]
	v_mfma_f32_16x16x32_bf16 v[0:3], v[192:195], v[220:223], v[0:3]
	v_mfma_f32_16x16x32_bf16 v[52:55], v[188:191], v[208:211], v[52:55]
	v_mfma_f32_16x16x32_bf16 v[44:47], v[196:199], v[208:211], v[44:47]
	v_mfma_f32_16x16x32_bf16 v[36:39], v[188:191], v[212:215], v[36:39]
	v_mfma_f32_16x16x32_bf16 v[28:31], v[196:199], v[212:215], v[28:31]
	v_mfma_f32_16x16x32_bf16 v[20:23], v[188:191], v[228:231], v[20:23]
	v_mfma_f32_16x16x32_bf16 v[12:15], v[196:199], v[228:231], v[12:15]
	v_mfma_f32_16x16x32_bf16 v[4:7], v[188:191], v[232:235], v[4:7]
	v_mfma_f32_16x16x32_bf16 v[0:3], v[196:199], v[232:235], v[0:3]
	s_setprio 0
	s_barrier
	s_add_i32 s87, s87, 2
	s_add_u32 s4, s4, 0x100
	s_addc_u32 s5, s5, 0
	s_add_u32 s85, s85, 0x100
	s_addc_u32 s86, s86, 0
	s_cmp_gt_u32 s87, 29
	s_cbranch_scc0 .LBB0_1047
	s_and_b64 vcc, exec, s[34:35]
	s_cbranch_vccz .LBB0_1050
	s_barrier

.LBB0_1335:
	ds_read_b128 v[168:171], v151
	ds_read_b128 v[172:175], v152
	ds_read_b128 v[176:179], v153
	ds_read_b128 v[180:183], v154
	ds_read_b128 v[184:187], v155
	ds_read_b128 v[188:191], v156
	ds_read_b128 v[192:195], v157
	ds_read_b128 v[196:199], v158
	s_add_u32 s7, s4, 0xfff80080
	s_addc_u32 s26, s5, -1
	s_cmp_eq_u32 s72, 28
	s_cselect_b32 s47, s15, s26
	s_cselect_b32 s46, s68, s7
	s_cselect_b32 s43, s35, s71
	s_cselect_b32 s42, s69, s70
	s_add_i32 m0, s52, 0xc000
	ds_read_b128 v[200:203], v159
	ds_read_b128 v[204:207], v159 offset:2048
	ds_read_b128 v[208:211], v160
	ds_read_b128 v[212:215], v160 offset:2048
	ds_read_b128 v[216:219], v159 offset:4096
	ds_read_b128 v[220:223], v159 offset:6144
	ds_read_b128 v[228:231], v160 offset:4096
	ds_read_b128 v[232:235], v160 offset:6144
	global_load_lds_dwordx4 v136, s[4:5]
	s_add_i32 m0, s52, 0xe000
	s_nop 0
	global_load_lds_dwordx4 v138, s[4:5]
	s_waitcnt vmcnt(8)
	s_waitcnt lgkmcnt(0)
	s_barrier
	s_setprio 1
	s_waitcnt lgkmcnt(0)
	v_mfma_f32_16x16x32_bf16 v[124:127], v[168:171], v[200:203], v[124:127]
	v_mfma_f32_16x16x32_bf16 v[116:119], v[176:179], v[200:203], v[116:119]
	v_mfma_f32_16x16x32_bf16 v[108:111], v[168:171], v[204:207], v[108:111]
	v_mfma_f32_16x16x32_bf16 v[100:103], v[176:179], v[204:207], v[100:103]
	v_mfma_f32_16x16x32_bf16 v[92:95], v[168:171], v[216:219], v[92:95]
	v_mfma_f32_16x16x32_bf16 v[84:87], v[176:179], v[216:219], v[84:87]
	v_mfma_f32_16x16x32_bf16 v[76:79], v[168:171], v[220:223], v[76:79]
	v_mfma_f32_16x16x32_bf16 v[68:71], v[176:179], v[220:223], v[68:71]
	v_mfma_f32_16x16x32_bf16 v[124:127], v[172:175], v[208:211], v[124:127]
	v_mfma_f32_16x16x32_bf16 v[116:119], v[180:183], v[208:211], v[116:119]
	v_mfma_f32_16x16x32_bf16 v[108:111], v[172:175], v[212:215], v[108:111]
	v_mfma_f32_16x16x32_bf16 v[100:103], v[180:183], v[212:215], v[100:103]
	v_mfma_f32_16x16x32_bf16 v[92:95], v[172:175], v[228:231], v[92:95]
	v_mfma_f32_16x16x32_bf16 v[84:87], v[180:183], v[228:231], v[84:87]
	v_mfma_f32_16x16x32_bf16 v[76:79], v[172:175], v[232:235], v[76:79]
	v_mfma_f32_16x16x32_bf16 v[68:71], v[180:183], v[232:235], v[68:71]
	s_setprio 0
	s_setprio 1
	v_mfma_f32_16x16x32_bf16 v[120:123], v[184:187], v[200:203], v[120:123]
	v_mfma_f32_16x16x32_bf16 v[112:115], v[192:195], v[200:203], v[112:115]
	v_mfma_f32_16x16x32_bf16 v[104:107], v[184:187], v[204:207], v[104:107]
	v_mfma_f32_16x16x32_bf16 v[96:99], v[192:195], v[204:207], v[96:99]
	v_mfma_f32_16x16x32_bf16 v[88:91], v[184:187], v[216:219], v[88:91]
	v_mfma_f32_16x16x32_bf16 v[80:83], v[192:195], v[216:219], v[80:83]
	v_mfma_f32_16x16x32_bf16 v[72:75], v[184:187], v[220:223], v[72:75]
	v_mfma_f32_16x16x32_bf16 v[64:67], v[192:195], v[220:223], v[64:67]
	v_mfma_f32_16x16x32_bf16 v[120:123], v[188:191], v[208:211], v[120:123]
	v_mfma_f32_16x16x32_bf16 v[112:115], v[196:199], v[208:211], v[112:115]
	v_mfma_f32_16x16x32_bf16 v[104:107], v[188:191], v[212:215], v[104:107]
	v_mfma_f32_16x16x32_bf16 v[96:99], v[196:199], v[212:215], v[96:99]
	v_mfma_f32_16x16x32_bf16 v[88:91], v[188:191], v[228:231], v[88:91]
	v_mfma_f32_16x16x32_bf16 v[80:83], v[196:199], v[228:231], v[80:83]
	v_mfma_f32_16x16x32_bf16 v[72:75], v[188:191], v[232:235], v[72:75]
	v_mfma_f32_16x16x32_bf16 v[64:67], v[196:199], v[232:235], v[64:67]
	s_setprio 0
	s_barrier
	s_add_i32 s7, s61, s50
	s_mov_b32 m0, s7
	ds_read_b128 v[200:203], v159 offset:16384
	ds_read_b128 v[204:207], v159 offset:18432
	ds_read_b128 v[208:211], v160 offset:16384
	ds_read_b128 v[212:215], v160 offset:18432
	ds_read_b128 v[216:219], v159 offset:20480
	ds_read_b128 v[220:223], v159 offset:22528
	ds_read_b128 v[228:231], v160 offset:20480
	ds_read_b128 v[232:235], v160 offset:22528
	global_load_lds_dwordx4 v132, s[42:43]
	s_add_i32 m0, s7, 0x2000
	s_add_u32 s26, s42, 0x80000
	s_addc_u32 s27, s43, 0
	s_add_i32 s7, s62, s50
	global_load_lds_dwordx4 v128, s[42:43]
	s_mov_b32 m0, s7
	s_nop 0
	global_load_lds_dwordx4 v132, s[26:27]
	s_add_i32 m0, s7, 0x2000
	s_nop 0
	global_load_lds_dwordx4 v128, s[26:27]
	s_mov_b32 m0, s52
	s_nop 0
	global_load_lds_dwordx4 v134, s[46:47]
	s_mov_b32 m0, s53
	s_nop 0
	global_load_lds_dwordx4 v130, s[46:47]
	s_waitcnt vmcnt(8)
	s_waitcnt lgkmcnt(0)
	s_barrier
	s_setprio 1
	s_waitcnt lgkmcnt(0)
	v_mfma_f32_16x16x32_bf16 v[60:63], v[168:171], v[200:203], v[60:63]
	v_mfma_f32_16x16x32_bf16 v[52:55], v[176:179], v[200:203], v[52:55]
	v_mfma_f32_16x16x32_bf16 v[44:47], v[168:171], v[204:207], v[44:47]
	v_mfma_f32_16x16x32_bf16 v[36:39], v[176:179], v[204:207], v[36:39]
	v_mfma_f32_16x16x32_bf16 v[28:31], v[168:171], v[216:219], v[28:31]
	v_mfma_f32_16x16x32_bf16 v[20:23], v[176:179], v[216:219], v[20:23]
	v_mfma_f32_16x16x32_bf16 v[12:15], v[168:171], v[220:223], v[12:15]
	v_mfma_f32_16x16x32_bf16 v[4:7], v[176:179], v[220:223], v[4:7]
	v_mfma_f32_16x16x32_bf16 v[60:63], v[172:175], v[208:211], v[60:63]
	v_mfma_f32_16x16x32_bf16 v[52:55], v[180:183], v[208:211], v[52:55]
	v_mfma_f32_16x16x32_bf16 v[44:47], v[172:175], v[212:215], v[44:47]
	v_mfma_f32_16x16x32_bf16 v[36:39], v[180:183], v[212:215], v[36:39]
	v_mfma_f32_16x16x32_bf16 v[28:31], v[172:175], v[228:231], v[28:31]
	v_mfma_f32_16x16x32_bf16 v[20:23], v[180:183], v[228:231], v[20:23]
	v_mfma_f32_16x16x32_bf16 v[12:15], v[172:175], v[232:235], v[12:15]
	v_mfma_f32_16x16x32_bf16 v[4:7], v[180:183], v[232:235], v[4:7]
	s_setprio 0
	s_setprio 1
	v_mfma_f32_16x16x32_bf16 v[56:59], v[184:187], v[200:203], v[56:59]
	v_mfma_f32_16x16x32_bf16 v[48:51], v[192:195], v[200:203], v[48:51]
	v_mfma_f32_16x16x32_bf16 v[40:43], v[184:187], v[204:207], v[40:43]
	v_mfma_f32_16x16x32_bf16 v[32:35], v[192:195], v[204:207], v[32:35]
	v_mfma_f32_16x16x32_bf16 v[24:27], v[184:187], v[216:219], v[24:27]
	v_mfma_f32_16x16x32_bf16 v[16:19], v[192:195], v[216:219], v[16:19]
	v_mfma_f32_16x16x32_bf16 v[8:11], v[184:187], v[220:223], v[8:11]
	v_mfma_f32_16x16x32_bf16 v[0:3], v[192:195], v[220:223], v[0:3]
	v_mfma_f32_16x16x32_bf16 v[56:59], v[188:191], v[208:211], v[56:59]
	v_mfma_f32_16x16x32_bf16 v[48:51], v[196:199], v[208:211], v[48:51]
	v_mfma_f32_16x16x32_bf16 v[40:43], v[188:191], v[212:215], v[40:43]
	v_mfma_f32_16x16x32_bf16 v[32:35], v[196:199], v[212:215], v[32:35]
	v_mfma_f32_16x16x32_bf16 v[24:27], v[188:191], v[228:231], v[24:27]
	v_mfma_f32_16x16x32_bf16 v[16:19], v[196:199], v[228:231], v[16:19]
	v_mfma_f32_16x16x32_bf16 v[8:11], v[188:191], v[232:235], v[8:11]
	v_mfma_f32_16x16x32_bf16 v[0:3], v[196:199], v[232:235], v[0:3]
	s_setprio 0
	s_barrier
	s_add_i32 s7, 0, 0x18000
	v_add_u32_e32 v167, s7, v146
	v_add_u32_e32 v172, s7, v147
	s_add_i32 s73, 0, 0x1c000
	ds_read_b128 v[168:171], v167
	ds_read_b128 v[172:175], v172
	ds_read_b128 v[176:179], v161
	ds_read_b128 v[180:183], v162
	v_add_u32_e32 v167, s73, v146
	v_add_u32_e32 v188, s73, v147
	ds_read_b128 v[184:187], v167
	ds_read_b128 v[188:191], v188
	ds_read_b128 v[192:195], v163
	ds_read_b128 v[196:199], v164
	s_add_u32 s26, s46, 0x80000
	s_addc_u32 s27, s47, 0
	s_mov_b32 m0, s54
	ds_read_b128 v[200:203], v159 offset:32768
	ds_read_b128 v[204:207], v159 offset:34816
	ds_read_b128 v[208:211], v160 offset:32768
	ds_read_b128 v[212:215], v160 offset:34816
	ds_read_b128 v[216:219], v159 offset:36864
	ds_read_b128 v[220:223], v159 offset:38912
	ds_read_b128 v[228:231], v160 offset:36864
	ds_read_b128 v[232:235], v160 offset:38912
	global_load_lds_dwordx4 v134, s[26:27]
	s_mov_b32 m0, s55
	s_nop 0
	global_load_lds_dwordx4 v130, s[26:27]
	s_waitcnt vmcnt(8)
	s_waitcnt lgkmcnt(0)
	s_barrier
	s_setprio 1
	s_waitcnt lgkmcnt(0)
	v_mfma_f32_16x16x32_bf16 v[124:127], v[168:171], v[200:203], v[124:127]
	v_mfma_f32_16x16x32_bf16 v[116:119], v[176:179], v[200:203], v[116:119]
	v_mfma_f32_16x16x32_bf16 v[108:111], v[168:171], v[204:207], v[108:111]
	v_mfma_f32_16x16x32_bf16 v[100:103], v[176:179], v[204:207], v[100:103]
	v_mfma_f32_16x16x32_bf16 v[92:95], v[168:171], v[216:219], v[92:95]
	v_mfma_f32_16x16x32_bf16 v[84:87], v[176:179], v[216:219], v[84:87]
	v_mfma_f32_16x16x32_bf16 v[76:79], v[168:171], v[220:223], v[76:79]
	v_mfma_f32_16x16x32_bf16 v[68:71], v[176:179], v[220:223], v[68:71]
	v_mfma_f32_16x16x32_bf16 v[124:127], v[172:175], v[208:211], v[124:127]
	v_mfma_f32_16x16x32_bf16 v[116:119], v[180:183], v[208:211], v[116:119]
	v_mfma_f32_16x16x32_bf16 v[108:111], v[172:175], v[212:215], v[108:111]
	v_mfma_f32_16x16x32_bf16 v[100:103], v[180:183], v[212:215], v[100:103]
	v_mfma_f32_16x16x32_bf16 v[92:95], v[172:175], v[228:231], v[92:95]
	v_mfma_f32_16x16x32_bf16 v[84:87], v[180:183], v[228:231], v[84:87]
	v_mfma_f32_16x16x32_bf16 v[76:79], v[172:175], v[232:235], v[76:79]
	v_mfma_f32_16x16x32_bf16 v[68:71], v[180:183], v[232:235], v[68:71]
	s_setprio 0
	s_setprio 1
	v_mfma_f32_16x16x32_bf16 v[120:123], v[184:187], v[200:203], v[120:123]
	v_mfma_f32_16x16x32_bf16 v[112:115], v[192:195], v[200:203], v[112:115]
	v_mfma_f32_16x16x32_bf16 v[104:107], v[184:187], v[204:207], v[104:107]
	v_mfma_f32_16x16x32_bf16 v[96:99], v[192:195], v[204:207], v[96:99]
	v_mfma_f32_16x16x32_bf16 v[88:91], v[184:187], v[216:219], v[88:91]
	v_mfma_f32_16x16x32_bf16 v[80:83], v[192:195], v[216:219], v[80:83]
	v_mfma_f32_16x16x32_bf16 v[72:75], v[184:187], v[220:223], v[72:75]
	v_mfma_f32_16x16x32_bf16 v[64:67], v[192:195], v[220:223], v[64:67]
	v_mfma_f32_16x16x32_bf16 v[120:123], v[188:191], v[208:211], v[120:123]
	v_mfma_f32_16x16x32_bf16 v[112:115], v[196:199], v[208:211], v[112:115]
	v_mfma_f32_16x16x32_bf16 v[104:107], v[188:191], v[212:215], v[104:107]
	v_mfma_f32_16x16x32_bf16 v[96:99], v[196:199], v[212:215], v[96:99]
	v_mfma_f32_16x16x32_bf16 v[88:91], v[188:191], v[228:231], v[88:91]
	v_mfma_f32_16x16x32_bf16 v[80:83], v[196:199], v[228:231], v[80:83]
	v_mfma_f32_16x16x32_bf16 v[72:75], v[188:191], v[232:235], v[72:75]
	v_mfma_f32_16x16x32_bf16 v[64:67], v[196:199], v[232:235], v[64:67]
	s_setprio 0
	s_barrier
	s_add_i32 s7, s7, s50
	s_add_i32 m0, s7, 0xffffff80
	ds_read_b128 v[200:203], v159 offset:49152
	ds_read_b128 v[204:207], v159 offset:51200
	ds_read_b128 v[208:211], v160 offset:49152
	ds_read_b128 v[212:215], v160 offset:51200
	ds_read_b128 v[216:219], v159 offset:53248
	ds_read_b128 v[220:223], v159 offset:55296
	ds_read_b128 v[228:231], v160 offset:53248
	ds_read_b128 v[232:235], v160 offset:55296
	global_load_lds_dwordx4 v132, s[42:43] offset:128
	s_add_i32 m0, s7, 0x1f80
	s_add_u32 s26, s42, 0x80080
	s_addc_u32 s27, s43, 0
	s_add_i32 s7, s73, s50
	global_load_lds_dwordx4 v128, s[42:43] offset:128
	s_mov_b32 m0, s7
	s_nop 0
	global_load_lds_dwordx4 v132, s[26:27]
	s_add_i32 m0, s7, 0x2000
	s_nop 0
	global_load_lds_dwordx4 v128, s[26:27]
	s_add_i32 m0, s57, 0xffffff80
	s_nop 0
	global_load_lds_dwordx4 v134, s[46:47] offset:128
	s_add_i32 m0, s58, 0xffffff80
	s_nop 0
	global_load_lds_dwordx4 v130, s[46:47] offset:128
	s_waitcnt vmcnt(8)
	s_waitcnt lgkmcnt(0)
	s_barrier
	s_setprio 1
	s_waitcnt lgkmcnt(0)
	v_mfma_f32_16x16x32_bf16 v[60:63], v[168:171], v[200:203], v[60:63]
	v_mfma_f32_16x16x32_bf16 v[52:55], v[176:179], v[200:203], v[52:55]
	v_mfma_f32_16x16x32_bf16 v[44:47], v[168:171], v[204:207], v[44:47]
	v_mfma_f32_16x16x32_bf16 v[36:39], v[176:179], v[204:207], v[36:39]
	v_mfma_f32_16x16x32_bf16 v[28:31], v[168:171], v[216:219], v[28:31]
	v_mfma_f32_16x16x32_bf16 v[20:23], v[176:179], v[216:219], v[20:23]
	v_mfma_f32_16x16x32_bf16 v[12:15], v[168:171], v[220:223], v[12:15]
	v_mfma_f32_16x16x32_bf16 v[4:7], v[176:179], v[220:223], v[4:7]
	v_mfma_f32_16x16x32_bf16 v[60:63], v[172:175], v[208:211], v[60:63]
	v_mfma_f32_16x16x32_bf16 v[52:55], v[180:183], v[208:211], v[52:55]
	v_mfma_f32_16x16x32_bf16 v[44:47], v[172:175], v[212:215], v[44:47]
	v_mfma_f32_16x16x32_bf16 v[36:39], v[180:183], v[212:215], v[36:39]
	v_mfma_f32_16x16x32_bf16 v[28:31], v[172:175], v[228:231], v[28:31]
	v_mfma_f32_16x16x32_bf16 v[20:23], v[180:183], v[228:231], v[20:23]
	v_mfma_f32_16x16x32_bf16 v[12:15], v[172:175], v[232:235], v[12:15]
	v_mfma_f32_16x16x32_bf16 v[4:7], v[180:183], v[232:235], v[4:7]
	s_setprio 0
	s_setprio 1
	v_mfma_f32_16x16x32_bf16 v[56:59], v[184:187], v[200:203], v[56:59]
	v_mfma_f32_16x16x32_bf16 v[48:51], v[192:195], v[200:203], v[48:51]
	v_mfma_f32_16x16x32_bf16 v[40:43], v[184:187], v[204:207], v[40:43]
	v_mfma_f32_16x16x32_bf16 v[32:35], v[192:195], v[204:207], v[32:35]
	v_mfma_f32_16x16x32_bf16 v[24:27], v[184:187], v[216:219], v[24:27]
	v_mfma_f32_16x16x32_bf16 v[16:19], v[192:195], v[216:219], v[16:19]
	v_mfma_f32_16x16x32_bf16 v[8:11], v[184:187], v[220:223], v[8:11]
	v_mfma_f32_16x16x32_bf16 v[0:3], v[192:195], v[220:223], v[0:3]
	v_mfma_f32_16x16x32_bf16 v[56:59], v[188:191], v[208:211], v[56:59]
	v_mfma_f32_16x16x32_bf16 v[48:51], v[196:199], v[208:211], v[48:51]
	v_mfma_f32_16x16x32_bf16 v[40:43], v[188:191], v[212:215], v[40:43]
	v_mfma_f32_16x16x32_bf16 v[32:35], v[196:199], v[212:215], v[32:35]
	v_mfma_f32_16x16x32_bf16 v[24:27], v[188:191], v[228:231], v[24:27]
	v_mfma_f32_16x16x32_bf16 v[16:19], v[196:199], v[228:231], v[16:19]
	v_mfma_f32_16x16x32_bf16 v[8:11], v[188:191], v[232:235], v[8:11]
	v_mfma_f32_16x16x32_bf16 v[0:3], v[196:199], v[232:235], v[0:3]
	s_setprio 0
	s_barrier
	s_add_i32 s72, s72, 2
	s_add_u32 s4, s4, 0x100
	s_addc_u32 s5, s5, 0
	s_add_u32 s70, s70, 0x100
	s_addc_u32 s71, s71, 0
	s_cmp_gt_u32 s72, 29
	s_cbranch_scc0 .LBB0_1335
	s_and_b64 vcc, exec, s[30:31]
	s_cbranch_vccz .LBB0_1338
	s_barrier
